# adds hand-written row loops for the other two norm phases and the prologue prenorm, and per-item load prefetch in the gated-conv prep loop
# speedup vs baseline: 1.0135x; 1.0135x over previous
; __device__ __forceinline__ unsigned cvt_pk_bf16(float lo, float hi) { f32x2_t v = {lo, hi}; bf16x2_t b = __builtin_convertvector(v, bf16x2_t); return __builtin_bit_cast(unsigned, b); }
; __device__ __forceinline__ void prenorm_rows(const Ctx& C, const float* x, const float* g, bf16_t* h) {
;     for (int m = C.gw; m < T_; m += C.NGW) {
;         const f32x4* xr = (const f32x4*)(x + (size_t)m * DM) + C.lane;
;         f32x4 v[4]; float s = 0.f;
; #pragma unroll
;         for (int j = 0; j < 4; ++j) { v[j] = xr[64 * j]; s += (v[j].x * v[j].x + v[j].y * v[j].y) + (v[j].z * v[j].z + v[j].w * v[j].w); }
;         const float rstd = rsqrtf(wave_sum(s) * (1.f / DM) + EPS);
;         u32x2* o = (u32x2*)(h + (size_t)m * DM) + C.lane;
; #pragma unroll
;         for (int j = 0; j < 4; ++j) { const f32x4 gg = ((const f32x4*)g)[C.lane + 64 * j]; u32x2 w; w.x = cvt_pk_bf16(v[j].x * rstd * gg.x, v[j].y * rstd * gg.y); w.y = cvt_pk_bf16(v[j].z * rstd * gg.z, v[j].w * rstd * gg.w); o[64 * j] = w; }
.LBB0_121:
	global_load_dwordx4 v[100:103], v[4:5], off
	global_load_dwordx4 v[104:107], v[4:5], off offset:1024
	global_load_dwordx4 v[108:111], v[4:5], off offset:2048
	global_load_dwordx4 v[112:115], v[4:5], off offset:3072
	s_lshl_b64 s[10:11], s[4:5], 1
	s_lshl_b64 s[12:13], s[0:1], 1
.Lpn_loop:
	s_add_i32 s3, s22, s70
	s_cmp_lt_i32 s3, 0x8000
	s_cselect_b64 s[36:37], -1, 0
	s_cselect_b32 s38, s4, 0
	s_cselect_b32 s39, s5, 0
	v_lshl_add_u64 v[36:37], v[2:3], 0, s[38:39]
	s_cselect_b32 s38, s0, 0
	s_cselect_b32 s39, s1, 0
	v_lshl_add_u64 v[38:39], v[0:1], 0, s[38:39]
	global_load_dwordx4 v[40:43], v[2:3], off offset:-3072
	global_load_dwordx4 v[44:47], v[2:3], off offset:-2048
	global_load_dwordx4 v[48:51], v[2:3], off offset:-1024
	global_load_dwordx4 v[52:55], v[2:3], off offset:0
	global_load_dwordx4 v[56:59], v[36:37], off offset:-3072
	global_load_dwordx4 v[60:63], v[36:37], off offset:-2048
	global_load_dwordx4 v[64:67], v[36:37], off offset:-1024
	global_load_dwordx4 v[68:71], v[36:37], off offset:0
	s_waitcnt vmcnt(4)
	v_mul_f32_e32 v14, v41, v41
	v_mul_f32_e32 v15, v43, v43
	v_mul_f32_e32 v16, v45, v45
	v_mul_f32_e32 v17, v47, v47
	v_mul_f32_e32 v18, v49, v49
	v_mul_f32_e32 v19, v51, v51
	v_mul_f32_e32 v20, v53, v53
	v_mul_f32_e32 v21, v55, v55
	v_fmac_f32_e32 v14, v40, v40
	v_fmac_f32_e32 v15, v42, v42
	v_fmac_f32_e32 v16, v44, v44
	v_fmac_f32_e32 v17, v46, v46
	v_fmac_f32_e32 v18, v48, v48
	v_fmac_f32_e32 v19, v50, v50
	v_fmac_f32_e32 v20, v52, v52
	v_fmac_f32_e32 v21, v54, v54
	v_add_f32_e32 v14, v14, v15
	v_add_f32_e32 v16, v16, v17
	v_add_f32_e32 v18, v18, v19
	v_add_f32_e32 v20, v20, v21
	v_add_f32_e32 v22, v14, v16
	v_add_f32_e32 v22, v18, v22
	v_add_f32_e32 v22, v20, v22
	s_nop 1
	v_add_f32_dpp v22, v22, v22 quad_perm:[1,0,3,2] row_mask:0xf bank_mask:0xf bound_ctrl:1
	s_nop 1
	v_add_f32_dpp v22, v22, v22 quad_perm:[2,3,0,1] row_mask:0xf bank_mask:0xf bound_ctrl:1
	s_nop 1
	v_add_f32_dpp v22, v22, v22 row_half_mirror row_mask:0xf bank_mask:0xf bound_ctrl:1
	s_nop 1
	v_add_f32_dpp v22, v22, v22 row_mirror row_mask:0xf bank_mask:0xf bound_ctrl:1
	v_mov_b32_e32 v23, v22
	s_nop 1
	v_permlane16_swap_b32_e32 v22, v23
	v_add_f32_e32 v22, v22, v23
	v_mov_b32_e32 v23, v22
	s_nop 1
	v_permlane32_swap_b32_e32 v22, v23
	v_add_f32_e32 v22, v22, v23
	v_fmamk_f32 v22, v22, 0x3a800000, v6
	v_mul_f32_e32 v23, 0x4b800000, v22
	v_cmp_gt_f32_e32 vcc, s2, v22
	s_nop 1
	v_cndmask_b32_e32 v22, v22, v23, vcc
	v_rsq_f32_e32 v22, v22
	s_nop 0
	v_mul_f32_e32 v23, 0x45800000, v22
	v_cndmask_b32_e32 v22, v22, v23, vcc
	v_mul_f32_e32 v24, v40, v22
	v_mul_f32_e32 v25, v41, v22
	v_mul_f32_e32 v26, v42, v22
	v_mul_f32_e32 v27, v43, v22
	v_mul_f32_e32 v24, v100, v24
	v_mul_f32_e32 v25, v101, v25
	v_mul_f32_e32 v26, v102, v26
	v_mul_f32_e32 v27, v103, v27
	v_cvt_pk_bf16_f32 v40, v24, v25
	v_cvt_pk_bf16_f32 v41, v26, v27
	v_mul_f32_e32 v24, v44, v22
	v_mul_f32_e32 v25, v45, v22
	v_mul_f32_e32 v26, v46, v22
	v_mul_f32_e32 v27, v47, v22
	v_mul_f32_e32 v24, v104, v24
	v_mul_f32_e32 v25, v105, v25
	v_mul_f32_e32 v26, v106, v26
	v_mul_f32_e32 v27, v107, v27
	v_cvt_pk_bf16_f32 v44, v24, v25
	v_cvt_pk_bf16_f32 v45, v26, v27
	v_mul_f32_e32 v24, v48, v22
	v_mul_f32_e32 v25, v49, v22
	v_mul_f32_e32 v26, v50, v22
	v_mul_f32_e32 v27, v51, v22
	v_mul_f32_e32 v24, v108, v24
	v_mul_f32_e32 v25, v109, v25
	v_mul_f32_e32 v26, v110, v26
	v_mul_f32_e32 v27, v111, v27
	v_cvt_pk_bf16_f32 v48, v24, v25
	v_cvt_pk_bf16_f32 v49, v26, v27
	v_mul_f32_e32 v24, v52, v22
	v_mul_f32_e32 v25, v53, v22
	v_mul_f32_e32 v26, v54, v22
	v_mul_f32_e32 v27, v55, v22
	v_mul_f32_e32 v24, v112, v24
	v_mul_f32_e32 v25, v113, v25
	v_mul_f32_e32 v26, v114, v26
	v_mul_f32_e32 v27, v115, v27
	v_cvt_pk_bf16_f32 v52, v24, v25
	v_cvt_pk_bf16_f32 v53, v26, v27
	s_and_b64 vcc, exec, s[36:37]
	s_cbranch_vccz .Lpn_skipB
	s_waitcnt vmcnt(0)
	v_mul_f32_e32 v14, v57, v57
	v_mul_f32_e32 v15, v59, v59
	v_mul_f32_e32 v16, v61, v61
	v_mul_f32_e32 v17, v63, v63
	v_mul_f32_e32 v18, v65, v65
	v_mul_f32_e32 v19, v67, v67
	v_mul_f32_e32 v20, v69, v69
	v_mul_f32_e32 v21, v71, v71
	v_fmac_f32_e32 v14, v56, v56
	v_fmac_f32_e32 v15, v58, v58
	v_fmac_f32_e32 v16, v60, v60
	v_fmac_f32_e32 v17, v62, v62
	v_fmac_f32_e32 v18, v64, v64
	v_fmac_f32_e32 v19, v66, v66
	v_fmac_f32_e32 v20, v68, v68
	v_fmac_f32_e32 v21, v70, v70
	v_add_f32_e32 v14, v14, v15
	v_add_f32_e32 v16, v16, v17
	v_add_f32_e32 v18, v18, v19
	v_add_f32_e32 v20, v20, v21
	v_add_f32_e32 v22, v14, v16
	v_add_f32_e32 v22, v18, v22
	v_add_f32_e32 v22, v20, v22
	s_nop 1
	v_add_f32_dpp v22, v22, v22 quad_perm:[1,0,3,2] row_mask:0xf bank_mask:0xf bound_ctrl:1
	s_nop 1
	v_add_f32_dpp v22, v22, v22 quad_perm:[2,3,0,1] row_mask:0xf bank_mask:0xf bound_ctrl:1
	s_nop 1
	v_add_f32_dpp v22, v22, v22 row_half_mirror row_mask:0xf bank_mask:0xf bound_ctrl:1
	s_nop 1
	v_add_f32_dpp v22, v22, v22 row_mirror row_mask:0xf bank_mask:0xf bound_ctrl:1
	v_mov_b32_e32 v23, v22
	s_nop 1
	v_permlane16_swap_b32_e32 v22, v23
	v_add_f32_e32 v22, v22, v23
	v_mov_b32_e32 v23, v22
	s_nop 1
	v_permlane32_swap_b32_e32 v22, v23
	v_add_f32_e32 v22, v22, v23
	v_fmamk_f32 v22, v22, 0x3a800000, v6
	v_mul_f32_e32 v23, 0x4b800000, v22
	v_cmp_gt_f32_e32 vcc, s2, v22
	s_nop 1
	v_cndmask_b32_e32 v22, v22, v23, vcc
	v_rsq_f32_e32 v22, v22
	s_nop 0
	v_mul_f32_e32 v23, 0x45800000, v22
	v_cndmask_b32_e32 v22, v22, v23, vcc
	v_mul_f32_e32 v24, v56, v22
	v_mul_f32_e32 v25, v57, v22
	v_mul_f32_e32 v26, v58, v22
	v_mul_f32_e32 v27, v59, v22
	v_mul_f32_e32 v24, v100, v24
	v_mul_f32_e32 v25, v101, v25
	v_mul_f32_e32 v26, v102, v26
	v_mul_f32_e32 v27, v103, v27
	v_cvt_pk_bf16_f32 v56, v24, v25
	v_cvt_pk_bf16_f32 v57, v26, v27
	v_mul_f32_e32 v24, v60, v22
	v_mul_f32_e32 v25, v61, v22
	v_mul_f32_e32 v26, v62, v22
	v_mul_f32_e32 v27, v63, v22
	v_mul_f32_e32 v24, v104, v24
	v_mul_f32_e32 v25, v105, v25
	v_mul_f32_e32 v26, v106, v26
	v_mul_f32_e32 v27, v107, v27
	v_cvt_pk_bf16_f32 v60, v24, v25
	v_cvt_pk_bf16_f32 v61, v26, v27
	v_mul_f32_e32 v24, v64, v22
	v_mul_f32_e32 v25, v65, v22
	v_mul_f32_e32 v26, v66, v22
	v_mul_f32_e32 v27, v67, v22
	v_mul_f32_e32 v24, v108, v24
	v_mul_f32_e32 v25, v109, v25
	v_mul_f32_e32 v26, v110, v26
	v_mul_f32_e32 v27, v111, v27
	v_cvt_pk_bf16_f32 v64, v24, v25
	v_cvt_pk_bf16_f32 v65, v26, v27
	v_mul_f32_e32 v24, v68, v22
	v_mul_f32_e32 v25, v69, v22
	v_mul_f32_e32 v26, v70, v22
	v_mul_f32_e32 v27, v71, v22
	v_mul_f32_e32 v24, v112, v24
	v_mul_f32_e32 v25, v113, v25
	v_mul_f32_e32 v26, v114, v26
	v_mul_f32_e32 v27, v115, v27
	v_cvt_pk_bf16_f32 v68, v24, v25
	v_cvt_pk_bf16_f32 v69, v26, v27
; __device__ __forceinline__ unsigned cvt_pk_bf16(float lo, float hi) { f32x2_t v = {lo, hi}; bf16x2_t b = __builtin_convertvector(v, bf16x2_t); return __builtin_bit_cast(unsigned, b); }
; __device__ __forceinline__ void prenorm_rows(const Ctx& C, const float* x, const float* g, bf16_t* h) {
;     ...
;         u32x2* o = (u32x2*)(h + (size_t)m * DM) + C.lane;
; #pragma unroll
;         for (int j = 0; j < 4; ++j) { const f32x4 gg = ((const f32x4*)g)[C.lane + 64 * j]; u32x2 w; w.x = cvt_pk_bf16(v[j].x * rstd * gg.x, v[j].y * rstd * gg.y); w.y = cvt_pk_bf16(v[j].z * rstd * gg.z, v[j].w * rstd * gg.w); o[64 * j] = w; }
;     }
.Lpn_skipB:
	global_store_dwordx2 v[0:1], v[40:41], off offset:-1536
	global_store_dwordx2 v[0:1], v[44:45], off offset:-1024
	global_store_dwordx2 v[0:1], v[48:49], off offset:-512
	global_store_dwordx2 v[0:1], v[52:53], off offset:0
	s_and_b64 vcc, exec, s[36:37]
	s_cbranch_vccz .Lpn_skipBs
	global_store_dwordx2 v[38:39], v[56:57], off offset:-1536
	global_store_dwordx2 v[38:39], v[60:61], off offset:-1024
	global_store_dwordx2 v[38:39], v[64:65], off offset:-512
	global_store_dwordx2 v[38:39], v[68:69], off offset:0
.Lpn_skipBs:
	v_lshl_add_u64 v[2:3], v[2:3], 0, s[10:11]
	v_lshl_add_u64 v[0:1], v[0:1], 0, s[12:13]
	s_add_i32 s22, s3, s70
	s_cmp_lt_i32 s22, 0x8000
	s_cbranch_scc1 .Lpn_loop

; __device__ __forceinline__ float bf_lo(unsigned u) { return __uint_as_float(u << 16); }
; __device__ __forceinline__ float bf_hi(unsigned u) { return __uint_as_float(u & 0xffff0000u); }
; __device__ __forceinline__ void norm_phase(const Ctx& C, int w0, int nw, const float* xin, float* xout, const bf16_t* y, bf16_t* h, const float* gpost, const float* gpre, float coef) {
;     for (int m0 = w0; m0 < T_; m0 += 2 * nw) {
;         f32x4 xv[2][4]; u32x2 yw[2][4];
; #pragma unroll
;         for (int r = 0; r < 2; ++r) { const int m = (m0 + r * nw < T_) ? m0 + r * nw : m0; const f32x4* xr = (const f32x4*)(xin + (size_t)m * DM) + C.lane; const u32x2* yr = (const u32x2*)(y + (size_t)m * DM) + C.lane;
; #pragma unroll
;             for (int j = 0; j < 4; ++j) { xv[r][j] = xr[64 * j]; yw[r][j] = yr[64 * j]; } }
; #pragma unroll
;         for (int r = 0; r < 2; ++r) {
;             const int m = m0 + r * nw; if (m >= T_) break;
;             f32x4 yv[4]; float s = 0.f;
; #pragma unroll
;             for (int j = 0; j < 4; ++j) { const u32x2 w = yw[r][j]; yv[j] = (f32x4){bf_lo(w.x), bf_hi(w.x), bf_lo(w.y), bf_hi(w.y)};
;                 s += (yv[j].x * yv[j].x + yv[j].y * yv[j].y) + (yv[j].z * yv[j].z + yv[j].w * yv[j].w); }
;             const float rs = rsqrtf(wave_sum(s) * (1.f / DM) + EPS) * coef; float s2 = 0.f;
;             f32x4* xo = (f32x4*)(xout + (size_t)m * DM) + C.lane;
; #pragma unroll
;             for (int j = 0; j < 4; ++j) { const f32x4 gg = ((const f32x4*)gpost)[C.lane + 64 * j]; xv[r][j] = xv[r][j] + yv[j] * gg * rs; xo[64 * j] = xv[r][j];
;                 s2 += (xv[r][j].x * xv[r][j].x + xv[r][j].y * xv[r][j].y) + (xv[r][j].z * xv[r][j].z + xv[r][j].w * xv[r][j].w); }
.LBB0_326:
	global_load_dwordx4 v[100:103], v[44:45], off
	global_load_dwordx4 v[104:107], v[44:45], off offset:1024
	global_load_dwordx4 v[108:111], v[44:45], off offset:2048
	global_load_dwordx4 v[112:115], v[44:45], off offset:3072
	s_and_b64 vcc, exec, s[44:45]
	s_cbranch_vccz .Ln3_loop
	global_load_dwordx4 v[116:119], v[46:47], off
	global_load_dwordx4 v[120:123], v[46:47], off offset:1024
	global_load_dwordx4 v[124:127], v[46:47], off offset:2048
	global_load_dwordx4 v[128:131], v[46:47], off offset:3072
.Ln3_loop:
	s_ashr_i32 s5, s4, 31
	s_add_i32 s12, s4, s43
	s_cmp_lt_i32 s12, 0x8000
	s_cselect_b64 s[18:19], -1, 0
	s_cselect_b32 s0, s12, s4
	s_ashr_i32 s1, s0, 31
	s_lshl_b64 s[2:3], s[4:5], 11
	v_lshl_add_u64 v[4:5], v[40:41], 0, s[2:3]
	v_lshl_add_u64 v[10:11], v[40:41], 0, s[2:3]
	s_lshl_b64 s[2:3], s[4:5], 12
	v_lshl_add_u64 v[2:3], v[38:39], 0, s[2:3]
	v_lshl_add_u64 v[28:29], v[42:43], 0, s[2:3]
	s_lshl_b64 s[2:3], s[0:1], 11
	v_lshl_add_u64 v[8:9], v[40:41], 0, s[2:3]
	v_lshl_add_u64 v[12:13], v[40:41], 0, s[2:3]
	s_lshl_b64 s[2:3], s[0:1], 12
	v_lshl_add_u64 v[6:7], v[38:39], 0, s[2:3]
	v_lshl_add_u64 v[30:31], v[42:43], 0, s[2:3]
	global_load_dwordx2 v[160:161], v[4:5], off
	global_load_dwordx2 v[162:163], v[4:5], off offset:512
	global_load_dwordx2 v[164:165], v[4:5], off offset:1024
	global_load_dwordx2 v[166:167], v[4:5], off offset:1536
	global_load_dwordx4 v[144:147], v[2:3], off
	global_load_dwordx4 v[148:151], v[2:3], off offset:1024
	global_load_dwordx4 v[152:155], v[2:3], off offset:2048
	global_load_dwordx4 v[156:159], v[2:3], off offset:3072
	global_load_dwordx2 v[184:185], v[8:9], off
	global_load_dwordx2 v[186:187], v[8:9], off offset:512
	global_load_dwordx2 v[188:189], v[8:9], off offset:1024
	global_load_dwordx2 v[190:191], v[8:9], off offset:1536
	global_load_dwordx4 v[168:171], v[6:7], off
	global_load_dwordx4 v[172:175], v[6:7], off offset:1024
	global_load_dwordx4 v[176:179], v[6:7], off offset:2048
	global_load_dwordx4 v[180:183], v[6:7], off offset:3072
	s_waitcnt vmcnt(12)
	v_lshlrev_b32_e32 v48, 16, v160
	v_and_b32_e32 v49, 0xffff0000, v160
	v_lshlrev_b32_e32 v50, 16, v161
	v_and_b32_e32 v51, 0xffff0000, v161
	v_lshlrev_b32_e32 v52, 16, v162
	v_and_b32_e32 v53, 0xffff0000, v162
	v_lshlrev_b32_e32 v54, 16, v163
	v_and_b32_e32 v55, 0xffff0000, v163
	v_lshlrev_b32_e32 v56, 16, v164
	v_and_b32_e32 v57, 0xffff0000, v164
	v_lshlrev_b32_e32 v58, 16, v165
	v_and_b32_e32 v59, 0xffff0000, v165
	v_lshlrev_b32_e32 v60, 16, v166
	v_and_b32_e32 v61, 0xffff0000, v166
	v_lshlrev_b32_e32 v62, 16, v167
	v_and_b32_e32 v63, 0xffff0000, v167
	v_mul_f32_e32 v14, v49, v49
	v_mul_f32_e32 v15, v51, v51
	v_mul_f32_e32 v16, v53, v53
	v_mul_f32_e32 v17, v55, v55
	v_mul_f32_e32 v18, v57, v57
	v_mul_f32_e32 v19, v59, v59
	v_mul_f32_e32 v20, v61, v61
	v_mul_f32_e32 v21, v63, v63
	v_fmac_f32_e32 v14, v48, v48
	v_fmac_f32_e32 v15, v50, v50
	v_fmac_f32_e32 v16, v52, v52
	v_fmac_f32_e32 v17, v54, v54
	v_fmac_f32_e32 v18, v56, v56
	v_fmac_f32_e32 v19, v58, v58
	v_fmac_f32_e32 v20, v60, v60
	v_fmac_f32_e32 v21, v62, v62
	v_add_f32_e32 v14, v14, v15
	v_add_f32_e32 v16, v16, v17
	v_add_f32_e32 v18, v18, v19
	v_add_f32_e32 v20, v20, v21
	v_add_f32_e32 v22, v14, v16
	v_add_f32_e32 v22, v18, v22
	v_add_f32_e32 v22, v20, v22
	s_nop 1
	v_add_f32_dpp v22, v22, v22 quad_perm:[1,0,3,2] row_mask:0xf bank_mask:0xf bound_ctrl:1
	s_nop 1
	v_add_f32_dpp v22, v22, v22 quad_perm:[2,3,0,1] row_mask:0xf bank_mask:0xf bound_ctrl:1
	s_nop 1
	v_add_f32_dpp v22, v22, v22 row_half_mirror row_mask:0xf bank_mask:0xf bound_ctrl:1
	s_nop 1
	v_add_f32_dpp v22, v22, v22 row_mirror row_mask:0xf bank_mask:0xf bound_ctrl:1
	v_mov_b32_e32 v23, v22
	s_nop 1
	v_permlane16_swap_b32_e32 v22, v23
	v_add_f32_e32 v22, v22, v23
	v_mov_b32_e32 v23, v22
	s_nop 1
	v_permlane32_swap_b32_e32 v22, v23
	v_add_f32_e32 v22, v22, v23
	v_fmamk_f32 v22, v22, 0x3a800000, v248
	v_mul_f32_e32 v23, 0x4b800000, v22
	v_cmp_gt_f32_e32 vcc, s64, v22
	s_nop 1
	v_cndmask_b32_e32 v22, v22, v23, vcc
	v_rsq_f32_e32 v22, v22
	s_nop 0
	v_mul_f32_e32 v23, 0x45800000, v22
	v_cndmask_b32_e32 v22, v22, v23, vcc
	v_mul_f32_e32 v22, 0.5, v22
	s_waitcnt vmcnt(8)
	v_mul_f32_e32 v24, v48, v100
	v_mul_f32_e32 v25, v49, v101
	v_mul_f32_e32 v26, v50, v102
	v_mul_f32_e32 v27, v51, v103
	v_fmac_f32_e32 v144, v24, v22
	v_fmac_f32_e32 v145, v25, v22
	v_fmac_f32_e32 v146, v26, v22
	v_fmac_f32_e32 v147, v27, v22
	v_mul_f32_e32 v24, v52, v104
	v_mul_f32_e32 v25, v53, v105
	v_mul_f32_e32 v26, v54, v106
	v_mul_f32_e32 v27, v55, v107
	v_fmac_f32_e32 v148, v24, v22
	v_fmac_f32_e32 v149, v25, v22
	v_fmac_f32_e32 v150, v26, v22
	v_fmac_f32_e32 v151, v27, v22
	v_mul_f32_e32 v24, v56, v108
	v_mul_f32_e32 v25, v57, v109
	v_mul_f32_e32 v26, v58, v110
	v_mul_f32_e32 v27, v59, v111
	v_fmac_f32_e32 v152, v24, v22
	v_fmac_f32_e32 v153, v25, v22
	v_fmac_f32_e32 v154, v26, v22
	v_fmac_f32_e32 v155, v27, v22
	v_mul_f32_e32 v24, v60, v112
	v_mul_f32_e32 v25, v61, v113
	v_mul_f32_e32 v26, v62, v114
	v_mul_f32_e32 v27, v63, v115
	v_fmac_f32_e32 v156, v24, v22
	v_fmac_f32_e32 v157, v25, v22
	v_fmac_f32_e32 v158, v26, v22
	v_fmac_f32_e32 v159, v27, v22
	s_and_b64 vcc, exec, s[44:45]
	s_cbranch_vccz .Ln3_noh_A
; __device__ __forceinline__ unsigned cvt_pk_bf16(float lo, float hi) { f32x2_t v = {lo, hi}; bf16x2_t b = __builtin_convertvector(v, bf16x2_t); return __builtin_bit_cast(unsigned, b); }
; __device__ __forceinline__ float bf_lo(unsigned u) { return __uint_as_float(u << 16); }
; __device__ __forceinline__ float bf_hi(unsigned u) { return __uint_as_float(u & 0xffff0000u); }
; __device__ __forceinline__ void norm_phase(const Ctx& C, int w0, int nw, const float* xin, float* xout, const bf16_t* y, bf16_t* h, const float* gpost, const float* gpre, float coef) {
;     ...
;         for (int r = 0; r < 2; ++r) {
;             const int m = m0 + r * nw; if (m >= T_) break;
;             f32x4 yv[4]; float s = 0.f;
; #pragma unroll
;             for (int j = 0; j < 4; ++j) { const u32x2 w = yw[r][j]; yv[j] = (f32x4){bf_lo(w.x), bf_hi(w.x), bf_lo(w.y), bf_hi(w.y)};
;                 s += (yv[j].x * yv[j].x + yv[j].y * yv[j].y) + (yv[j].z * yv[j].z + yv[j].w * yv[j].w); }
;             const float rs = rsqrtf(wave_sum(s) * (1.f / DM) + EPS) * coef; float s2 = 0.f;
;             f32x4* xo = (f32x4*)(xout + (size_t)m * DM) + C.lane;
; #pragma unroll
;             for (int j = 0; j < 4; ++j) { const f32x4 gg = ((const f32x4*)gpost)[C.lane + 64 * j]; xv[r][j] = xv[r][j] + yv[j] * gg * rs; xo[64 * j] = xv[r][j];
;                 s2 += (xv[r][j].x * xv[r][j].x + xv[r][j].y * xv[r][j].y) + (xv[r][j].z * xv[r][j].z + xv[r][j].w * xv[r][j].w); }
;             if (gpre) {
;                 const float r2 = rsqrtf(wave_sum(s2) * (1.f / DM) + EPS);
;                 u32x2* o = (u32x2*)(h + (size_t)m * DM) + C.lane;
; #pragma unroll
;                 for (int j = 0; j < 4; ++j) { const f32x4 gg = ((const f32x4*)gpre)[C.lane + 64 * j]; u32x2 w; w.x = cvt_pk_bf16(xv[r][j].x * r2 * gg.x, xv[r][j].y * r2 * gg.y); w.y = cvt_pk_bf16(xv[r][j].z * r2 * gg.z, xv[r][j].w * r2 * gg.w); o[64 * j] = w; }
;             }
	v_mul_f32_e32 v14, v145, v145
	v_mul_f32_e32 v15, v147, v147
	v_mul_f32_e32 v16, v149, v149
	v_mul_f32_e32 v17, v151, v151
	v_mul_f32_e32 v18, v153, v153
	v_mul_f32_e32 v19, v155, v155
	v_mul_f32_e32 v20, v157, v157
	v_mul_f32_e32 v21, v159, v159
	v_fmac_f32_e32 v14, v144, v144
	v_fmac_f32_e32 v15, v146, v146
	v_fmac_f32_e32 v16, v148, v148
	v_fmac_f32_e32 v17, v150, v150
	v_fmac_f32_e32 v18, v152, v152
	v_fmac_f32_e32 v19, v154, v154
	v_fmac_f32_e32 v20, v156, v156
	v_fmac_f32_e32 v21, v158, v158
	v_add_f32_e32 v14, v14, v15
	v_add_f32_e32 v16, v16, v17
	v_add_f32_e32 v18, v18, v19
	v_add_f32_e32 v20, v20, v21
	v_add_f32_e32 v22, v14, v16
	v_add_f32_e32 v22, v18, v22
	v_add_f32_e32 v22, v20, v22
	s_nop 1
	v_add_f32_dpp v22, v22, v22 quad_perm:[1,0,3,2] row_mask:0xf bank_mask:0xf bound_ctrl:1
	s_nop 1
	v_add_f32_dpp v22, v22, v22 quad_perm:[2,3,0,1] row_mask:0xf bank_mask:0xf bound_ctrl:1
	s_nop 1
	v_add_f32_dpp v22, v22, v22 row_half_mirror row_mask:0xf bank_mask:0xf bound_ctrl:1
	s_nop 1
	v_add_f32_dpp v22, v22, v22 row_mirror row_mask:0xf bank_mask:0xf bound_ctrl:1
	v_mov_b32_e32 v23, v22
	s_nop 1
	v_permlane16_swap_b32_e32 v22, v23
	v_add_f32_e32 v22, v22, v23
	v_mov_b32_e32 v23, v22
	s_nop 1
	v_permlane32_swap_b32_e32 v22, v23
	v_add_f32_e32 v22, v22, v23
	v_fmamk_f32 v22, v22, 0x3a800000, v248
	v_mul_f32_e32 v23, 0x4b800000, v22
	v_cmp_gt_f32_e32 vcc, s64, v22
	s_nop 1
	v_cndmask_b32_e32 v22, v22, v23, vcc
	v_rsq_f32_e32 v22, v22
	s_nop 0
	v_mul_f32_e32 v23, 0x45800000, v22
	v_cndmask_b32_e32 v22, v22, v23, vcc
	v_mul_f32_e32 v24, v144, v22
	v_mul_f32_e32 v25, v145, v22
	v_mul_f32_e32 v26, v146, v22
	v_mul_f32_e32 v27, v147, v22
	v_mul_f32_e32 v24, v116, v24
	v_mul_f32_e32 v25, v117, v25
	v_mul_f32_e32 v26, v118, v26
	v_mul_f32_e32 v27, v119, v27
	v_cvt_pk_bf16_f32 v192, v24, v25
	v_cvt_pk_bf16_f32 v193, v26, v27
	v_mul_f32_e32 v24, v148, v22
	v_mul_f32_e32 v25, v149, v22
	v_mul_f32_e32 v26, v150, v22
	v_mul_f32_e32 v27, v151, v22
	v_mul_f32_e32 v24, v120, v24
	v_mul_f32_e32 v25, v121, v25
	v_mul_f32_e32 v26, v122, v26
	v_mul_f32_e32 v27, v123, v27
	v_cvt_pk_bf16_f32 v194, v24, v25
	v_cvt_pk_bf16_f32 v195, v26, v27
	v_mul_f32_e32 v24, v152, v22
	v_mul_f32_e32 v25, v153, v22
	v_mul_f32_e32 v26, v154, v22
	v_mul_f32_e32 v27, v155, v22
	v_mul_f32_e32 v24, v124, v24
	v_mul_f32_e32 v25, v125, v25
	v_mul_f32_e32 v26, v126, v26
	v_mul_f32_e32 v27, v127, v27
	v_cvt_pk_bf16_f32 v196, v24, v25
	v_cvt_pk_bf16_f32 v197, v26, v27
	v_mul_f32_e32 v24, v156, v22
	v_mul_f32_e32 v25, v157, v22
	v_mul_f32_e32 v26, v158, v22
	v_mul_f32_e32 v27, v159, v22
	v_mul_f32_e32 v24, v128, v24
	v_mul_f32_e32 v25, v129, v25
	v_mul_f32_e32 v26, v130, v26
	v_mul_f32_e32 v27, v131, v27
	v_cvt_pk_bf16_f32 v198, v24, v25
	v_cvt_pk_bf16_f32 v199, v26, v27
.Ln3_noh_A:
	s_and_b64 vcc, exec, s[18:19]
	s_cbranch_vccz .Ln3_skipB
	s_waitcnt vmcnt(4)
	v_lshlrev_b32_e32 v48, 16, v184
	v_and_b32_e32 v49, 0xffff0000, v184
	v_lshlrev_b32_e32 v50, 16, v185
	v_and_b32_e32 v51, 0xffff0000, v185
	v_lshlrev_b32_e32 v52, 16, v186
	v_and_b32_e32 v53, 0xffff0000, v186
	v_lshlrev_b32_e32 v54, 16, v187
	v_and_b32_e32 v55, 0xffff0000, v187
	v_lshlrev_b32_e32 v56, 16, v188
	v_and_b32_e32 v57, 0xffff0000, v188
	v_lshlrev_b32_e32 v58, 16, v189
	v_and_b32_e32 v59, 0xffff0000, v189
	v_lshlrev_b32_e32 v60, 16, v190
	v_and_b32_e32 v61, 0xffff0000, v190
	v_lshlrev_b32_e32 v62, 16, v191
	v_and_b32_e32 v63, 0xffff0000, v191
	v_mul_f32_e32 v14, v49, v49
	v_mul_f32_e32 v15, v51, v51
	v_mul_f32_e32 v16, v53, v53
	v_mul_f32_e32 v17, v55, v55
	v_mul_f32_e32 v18, v57, v57
	v_mul_f32_e32 v19, v59, v59
	v_mul_f32_e32 v20, v61, v61
	v_mul_f32_e32 v21, v63, v63
	v_fmac_f32_e32 v14, v48, v48
	v_fmac_f32_e32 v15, v50, v50
	v_fmac_f32_e32 v16, v52, v52
	v_fmac_f32_e32 v17, v54, v54
	v_fmac_f32_e32 v18, v56, v56
	v_fmac_f32_e32 v19, v58, v58
	v_fmac_f32_e32 v20, v60, v60
	v_fmac_f32_e32 v21, v62, v62
	v_add_f32_e32 v14, v14, v15
	v_add_f32_e32 v16, v16, v17
	v_add_f32_e32 v18, v18, v19
	v_add_f32_e32 v20, v20, v21
	v_add_f32_e32 v22, v14, v16
	v_add_f32_e32 v22, v18, v22
	v_add_f32_e32 v22, v20, v22
	s_nop 1
	v_add_f32_dpp v22, v22, v22 quad_perm:[1,0,3,2] row_mask:0xf bank_mask:0xf bound_ctrl:1
	s_nop 1
	v_add_f32_dpp v22, v22, v22 quad_perm:[2,3,0,1] row_mask:0xf bank_mask:0xf bound_ctrl:1
	s_nop 1
	v_add_f32_dpp v22, v22, v22 row_half_mirror row_mask:0xf bank_mask:0xf bound_ctrl:1
	s_nop 1
	v_add_f32_dpp v22, v22, v22 row_mirror row_mask:0xf bank_mask:0xf bound_ctrl:1
	v_mov_b32_e32 v23, v22
	s_nop 1
	v_permlane16_swap_b32_e32 v22, v23
	v_add_f32_e32 v22, v22, v23
	v_mov_b32_e32 v23, v22
	s_nop 1
	v_permlane32_swap_b32_e32 v22, v23
	v_add_f32_e32 v22, v22, v23
	v_fmamk_f32 v22, v22, 0x3a800000, v248
	v_mul_f32_e32 v23, 0x4b800000, v22
	v_cmp_gt_f32_e32 vcc, s64, v22
	s_nop 1
	v_cndmask_b32_e32 v22, v22, v23, vcc
	v_rsq_f32_e32 v22, v22
	s_nop 0
	v_mul_f32_e32 v23, 0x45800000, v22
	v_cndmask_b32_e32 v22, v22, v23, vcc
	v_mul_f32_e32 v22, 0.5, v22
	s_waitcnt vmcnt(0)
	v_mul_f32_e32 v24, v48, v100
	v_mul_f32_e32 v25, v49, v101
	v_mul_f32_e32 v26, v50, v102
	v_mul_f32_e32 v27, v51, v103
	v_fmac_f32_e32 v168, v24, v22
	v_fmac_f32_e32 v169, v25, v22
	v_fmac_f32_e32 v170, v26, v22
	v_fmac_f32_e32 v171, v27, v22
	v_mul_f32_e32 v24, v52, v104
	v_mul_f32_e32 v25, v53, v105
	v_mul_f32_e32 v26, v54, v106
	v_mul_f32_e32 v27, v55, v107
	v_fmac_f32_e32 v172, v24, v22
	v_fmac_f32_e32 v173, v25, v22
	v_fmac_f32_e32 v174, v26, v22
	v_fmac_f32_e32 v175, v27, v22
	v_mul_f32_e32 v24, v56, v108
	v_mul_f32_e32 v25, v57, v109
	v_mul_f32_e32 v26, v58, v110
	v_mul_f32_e32 v27, v59, v111
	v_fmac_f32_e32 v176, v24, v22
	v_fmac_f32_e32 v177, v25, v22
	v_fmac_f32_e32 v178, v26, v22
	v_fmac_f32_e32 v179, v27, v22
	v_mul_f32_e32 v24, v60, v112
	v_mul_f32_e32 v25, v61, v113
	v_mul_f32_e32 v26, v62, v114
	v_mul_f32_e32 v27, v63, v115
	v_fmac_f32_e32 v180, v24, v22
	v_fmac_f32_e32 v181, v25, v22
	v_fmac_f32_e32 v182, v26, v22
	v_fmac_f32_e32 v183, v27, v22
	s_and_b64 vcc, exec, s[44:45]
	s_cbranch_vccz .Ln3_noh_B
; __device__ __forceinline__ unsigned cvt_pk_bf16(float lo, float hi) { f32x2_t v = {lo, hi}; bf16x2_t b = __builtin_convertvector(v, bf16x2_t); return __builtin_bit_cast(unsigned, b); }
; __device__ __forceinline__ void norm_phase(const Ctx& C, int w0, int nw, const float* xin, float* xout, const bf16_t* y, bf16_t* h, const float* gpost, const float* gpre, float coef) {
;     ...
;             for (int j = 0; j < 4; ++j) { const f32x4 gg = ((const f32x4*)gpost)[C.lane + 64 * j]; xv[r][j] = xv[r][j] + yv[j] * gg * rs; xo[64 * j] = xv[r][j];
;                 s2 += (xv[r][j].x * xv[r][j].x + xv[r][j].y * xv[r][j].y) + (xv[r][j].z * xv[r][j].z + xv[r][j].w * xv[r][j].w); }
;             if (gpre) {
;                 const float r2 = rsqrtf(wave_sum(s2) * (1.f / DM) + EPS);
;                 u32x2* o = (u32x2*)(h + (size_t)m * DM) + C.lane;
; #pragma unroll
;                 for (int j = 0; j < 4; ++j) { const f32x4 gg = ((const f32x4*)gpre)[C.lane + 64 * j]; u32x2 w; w.x = cvt_pk_bf16(xv[r][j].x * r2 * gg.x, xv[r][j].y * r2 * gg.y); w.y = cvt_pk_bf16(xv[r][j].z * r2 * gg.z, xv[r][j].w * r2 * gg.w); o[64 * j] = w; }
;             }
;         }
;     }
	v_mul_f32_e32 v14, v169, v169
	v_mul_f32_e32 v15, v171, v171
	v_mul_f32_e32 v16, v173, v173
	v_mul_f32_e32 v17, v175, v175
	v_mul_f32_e32 v18, v177, v177
	v_mul_f32_e32 v19, v179, v179
	v_mul_f32_e32 v20, v181, v181
	v_mul_f32_e32 v21, v183, v183
	v_fmac_f32_e32 v14, v168, v168
	v_fmac_f32_e32 v15, v170, v170
	v_fmac_f32_e32 v16, v172, v172
	v_fmac_f32_e32 v17, v174, v174
	v_fmac_f32_e32 v18, v176, v176
	v_fmac_f32_e32 v19, v178, v178
	v_fmac_f32_e32 v20, v180, v180
	v_fmac_f32_e32 v21, v182, v182
	v_add_f32_e32 v14, v14, v15
	v_add_f32_e32 v16, v16, v17
	v_add_f32_e32 v18, v18, v19
	v_add_f32_e32 v20, v20, v21
	v_add_f32_e32 v22, v14, v16
	v_add_f32_e32 v22, v18, v22
	v_add_f32_e32 v22, v20, v22
	s_nop 1
	v_add_f32_dpp v22, v22, v22 quad_perm:[1,0,3,2] row_mask:0xf bank_mask:0xf bound_ctrl:1
	s_nop 1
	v_add_f32_dpp v22, v22, v22 quad_perm:[2,3,0,1] row_mask:0xf bank_mask:0xf bound_ctrl:1
	s_nop 1
	v_add_f32_dpp v22, v22, v22 row_half_mirror row_mask:0xf bank_mask:0xf bound_ctrl:1
	s_nop 1
	v_add_f32_dpp v22, v22, v22 row_mirror row_mask:0xf bank_mask:0xf bound_ctrl:1
	v_mov_b32_e32 v23, v22
	s_nop 1
	v_permlane16_swap_b32_e32 v22, v23
	v_add_f32_e32 v22, v22, v23
	v_mov_b32_e32 v23, v22
	s_nop 1
	v_permlane32_swap_b32_e32 v22, v23
	v_add_f32_e32 v22, v22, v23
	v_fmamk_f32 v22, v22, 0x3a800000, v248
	v_mul_f32_e32 v23, 0x4b800000, v22
	v_cmp_gt_f32_e32 vcc, s64, v22
	s_nop 1
	v_cndmask_b32_e32 v22, v22, v23, vcc
	v_rsq_f32_e32 v22, v22
	s_nop 0
	v_mul_f32_e32 v23, 0x45800000, v22
	v_cndmask_b32_e32 v22, v22, v23, vcc
	v_mul_f32_e32 v24, v168, v22
	v_mul_f32_e32 v25, v169, v22
	v_mul_f32_e32 v26, v170, v22
	v_mul_f32_e32 v27, v171, v22
	v_mul_f32_e32 v24, v116, v24
	v_mul_f32_e32 v25, v117, v25
	v_mul_f32_e32 v26, v118, v26
	v_mul_f32_e32 v27, v119, v27
	v_cvt_pk_bf16_f32 v200, v24, v25
	v_cvt_pk_bf16_f32 v201, v26, v27
	v_mul_f32_e32 v24, v172, v22
	v_mul_f32_e32 v25, v173, v22
	v_mul_f32_e32 v26, v174, v22
	v_mul_f32_e32 v27, v175, v22
	v_mul_f32_e32 v24, v120, v24
	v_mul_f32_e32 v25, v121, v25
	v_mul_f32_e32 v26, v122, v26
	v_mul_f32_e32 v27, v123, v27
	v_cvt_pk_bf16_f32 v202, v24, v25
	v_cvt_pk_bf16_f32 v203, v26, v27
	v_mul_f32_e32 v24, v176, v22
	v_mul_f32_e32 v25, v177, v22
	v_mul_f32_e32 v26, v178, v22
	v_mul_f32_e32 v27, v179, v22
	v_mul_f32_e32 v24, v124, v24
	v_mul_f32_e32 v25, v125, v25
	v_mul_f32_e32 v26, v126, v26
	v_mul_f32_e32 v27, v127, v27
	v_cvt_pk_bf16_f32 v204, v24, v25
	v_cvt_pk_bf16_f32 v205, v26, v27
	v_mul_f32_e32 v24, v180, v22
	v_mul_f32_e32 v25, v181, v22
	v_mul_f32_e32 v26, v182, v22
	v_mul_f32_e32 v27, v183, v22
	v_mul_f32_e32 v24, v128, v24
	v_mul_f32_e32 v25, v129, v25
	v_mul_f32_e32 v26, v130, v26
	v_mul_f32_e32 v27, v131, v27
	v_cvt_pk_bf16_f32 v206, v24, v25
	v_cvt_pk_bf16_f32 v207, v26, v27
.Ln3_noh_B:
.Ln3_skipB:
	global_store_dwordx4 v[28:29], v[144:147], off
	global_store_dwordx4 v[28:29], v[148:151], off offset:1024
	global_store_dwordx4 v[28:29], v[152:155], off offset:2048
	global_store_dwordx4 v[28:29], v[156:159], off offset:3072
	s_and_b64 vcc, exec, s[44:45]
	s_cbranch_vccz .Ln3_nohs_A
	global_store_dwordx2 v[10:11], v[192:193], off
	global_store_dwordx2 v[10:11], v[194:195], off offset:512
	global_store_dwordx2 v[10:11], v[196:197], off offset:1024
	global_store_dwordx2 v[10:11], v[198:199], off offset:1536
.Ln3_nohs_A:
	s_and_b64 vcc, exec, s[18:19]
	s_cbranch_vccz .Ln3_skipBs
	global_store_dwordx4 v[30:31], v[168:171], off
	global_store_dwordx4 v[30:31], v[172:175], off offset:1024
	global_store_dwordx4 v[30:31], v[176:179], off offset:2048
	global_store_dwordx4 v[30:31], v[180:183], off offset:3072
	s_and_b64 vcc, exec, s[44:45]
	s_cbranch_vccz .Ln3_nohs_B
	global_store_dwordx2 v[12:13], v[200:201], off
	global_store_dwordx2 v[12:13], v[202:203], off offset:512
	global_store_dwordx2 v[12:13], v[204:205], off offset:1024
	global_store_dwordx2 v[12:13], v[206:207], off offset:1536
.Ln3_nohs_B:
.Ln3_skipBs:
	s_add_i32 s4, s12, s43
	s_cmp_lt_i32 s4, 0x8000
	s_cbranch_scc1 .Ln3_loop

; __device__ __forceinline__ unsigned cvt_pk_bf16(float lo, float hi) { f32x2_t v = {lo, hi}; bf16x2_t b = __builtin_convertvector(v, bf16x2_t); return __builtin_bit_cast(unsigned, b); }
; __device__ __forceinline__ float bf_lo(unsigned u) { return __uint_as_float(u << 16); }
; __device__ __forceinline__ float bf_hi(unsigned u) { return __uint_as_float(u & 0xffff0000u); }
; __device__ __forceinline__ void prep_items(const Ctx& C, int l, int w0, int nw) {
;     ...
;             for (int tt = 0; tt < 8; ++tt) {
;                 const bf16_t* row = P + (size_t)(tok0 + tt) * PP + lane * 8;
;                 const u32x4 u = *(const u32x4*)row, bb = *(const u32x4*)(row + 512), cc = *(const u32x4*)(row + 1024);
;                 const float c0[8] = {bf_lo(u.x) * bf_lo(cc.x), bf_hi(u.x) * bf_hi(cc.x), bf_lo(u.y) * bf_lo(cc.y), bf_hi(u.y) * bf_hi(cc.y), bf_lo(u.z) * bf_lo(cc.z), bf_hi(u.z) * bf_hi(cc.z), bf_lo(u.w) * bf_lo(cc.w), bf_hi(u.w) * bf_hi(cc.w)};
;                 const float bv[8] = {bf_lo(bb.x), bf_hi(bb.x), bf_lo(bb.y), bf_hi(bb.y), bf_lo(bb.z), bf_hi(bb.z), bf_lo(bb.w), bf_hi(bb.w)};
;                 float o[8];
; #pragma unroll
;                 for (int e = 0; e < 8; ++e) { o[e] = bv[e] * (w[0][e] * c2[e] + w[1][e] * c1[e] + w[2][e] * c0[e]); c2[e] = c1[e]; c1[e] = c0[e]; }
;                 u32x4 ov; ov.x = cvt_pk_bf16(o[0], o[1]); ov.y = cvt_pk_bf16(o[2], o[3]); ov.z = cvt_pk_bf16(o[4], o[5]); ov.w = cvt_pk_bf16(o[6], o[7]);
;                 *(u32x4*)(Y + (size_t)(tok0 + tt) * YP + lane * 8) = ov;
.LBB0_474:
	s_add_i32 s6, s1, 2
	v_mad_i64_i32 v[30:31], s[10:11], s6, v233, v[26:27]
	s_waitcnt vmcnt(21)
	s_nop 1
	v_mov_b32_e32 v54, v98
	v_mov_b32_e32 v55, v99
	v_mov_b32_e32 v56, v100
	v_mov_b32_e32 v57, v101
	v_mov_b32_e32 v58, v102
	v_mov_b32_e32 v59, v103
	v_mov_b32_e32 v60, v104
	v_mov_b32_e32 v61, v105
	v_mov_b32_e32 v62, v106
	v_mov_b32_e32 v63, v107
	v_mov_b32_e32 v64, v108
	v_mov_b32_e32 v65, v109
	v_pk_mul_f32 v[44:45], v[6:7], v[44:45]
	v_pk_mul_f32 v[46:47], v[8:9], v[46:47]
	v_pk_fma_f32 v[44:45], v[14:15], v[32:33], v[44:45]
	v_pk_fma_f32 v[46:47], v[16:17], v[34:35], v[46:47]
	v_pk_mul_f32 v[48:49], v[2:3], v[48:49]
	v_pk_mul_f32 v[50:51], v[4:5], v[50:51]
	v_pk_fma_f32 v[48:49], v[10:11], v[36:37], v[48:49]
	v_pk_fma_f32 v[50:51], v[12:13], v[38:39], v[50:51]
	s_add_i32 s3, s3, s46
	v_lshlrev_b32_e32 v30, 16, v54
	v_and_b32_e32 v31, 0xffff0000, v54
	v_lshlrev_b32_e32 v40, 16, v62
	v_and_b32_e32 v41, 0xffff0000, v62
	v_pk_mul_f32 v[40:41], v[30:31], v[40:41]
	v_lshlrev_b32_e32 v30, 16, v58
	v_and_b32_e32 v31, 0xffff0000, v58
	v_pk_fma_f32 v[44:45], v[18:19], v[40:41], v[44:45]
	v_lshlrev_b32_e32 v54, 16, v63
	v_pk_mul_f32 v[30:31], v[44:45], v[30:31]
	v_lshlrev_b32_e32 v44, 16, v55
	v_and_b32_e32 v45, 0xffff0000, v55
	v_and_b32_e32 v55, 0xffff0000, v63
	v_pk_mul_f32 v[44:45], v[44:45], v[54:55]
	v_lshlrev_b32_e32 v54, 16, v59
	v_and_b32_e32 v55, 0xffff0000, v59
	v_pk_fma_f32 v[46:47], v[20:21], v[44:45], v[46:47]
	v_pk_mul_f32 v[66:67], v[14:15], v[40:41]
	v_pk_mul_f32 v[58:59], v[46:47], v[54:55]
	v_lshlrev_b32_e32 v46, 16, v56
	v_and_b32_e32 v47, 0xffff0000, v56
	v_lshlrev_b32_e32 v54, 16, v64
	v_and_b32_e32 v55, 0xffff0000, v64
	v_pk_mul_f32 v[46:47], v[46:47], v[54:55]
	v_lshlrev_b32_e32 v54, 16, v60
	v_and_b32_e32 v55, 0xffff0000, v60
	v_pk_fma_f32 v[48:49], v[22:23], v[46:47], v[48:49]
	v_pk_fma_f32 v[32:33], v[6:7], v[32:33], v[66:67]
	v_pk_mul_f32 v[62:63], v[48:49], v[54:55]
	v_lshlrev_b32_e32 v48, 16, v57
	v_and_b32_e32 v49, 0xffff0000, v57
	v_lshlrev_b32_e32 v54, 16, v65
	v_and_b32_e32 v55, 0xffff0000, v65
	v_pk_mul_f32 v[48:49], v[48:49], v[54:55]
	v_lshlrev_b32_e32 v54, 16, v61
	v_and_b32_e32 v55, 0xffff0000, v61
	v_pk_fma_f32 v[50:51], v[24:25], v[48:49], v[50:51]
	v_cvt_pk_bf16_f32 v56, v62, v63
	v_pk_mul_f32 v[50:51], v[50:51], v[54:55]
	v_cvt_pk_bf16_f32 v54, v30, v31
	v_cvt_pk_bf16_f32 v55, v58, v59
	v_cvt_pk_bf16_f32 v57, v50, v51
	v_mad_i64_i32 v[30:31], s[10:11], s6, v238, v[28:29]
	s_add_i32 s6, s1, 3
	global_store_dwordx4 v[30:31], v[54:57], off
	v_mad_i64_i32 v[30:31], s[10:11], s6, v233, v[26:27]
	s_waitcnt vmcnt(19)
	s_nop 1
	v_mov_b32_e32 v54, v110
	v_mov_b32_e32 v55, v111
	v_mov_b32_e32 v56, v112
	v_mov_b32_e32 v57, v113
	v_mov_b32_e32 v58, v114
	v_mov_b32_e32 v59, v115
	v_mov_b32_e32 v60, v116
	v_mov_b32_e32 v61, v117
	v_mov_b32_e32 v62, v118
	v_mov_b32_e32 v63, v119
	v_mov_b32_e32 v64, v120
	v_mov_b32_e32 v65, v121
	v_lshlrev_b32_e32 v30, 16, v54
	v_and_b32_e32 v31, 0xffff0000, v54
	v_lshlrev_b32_e32 v50, 16, v62
	v_and_b32_e32 v51, 0xffff0000, v62
	v_pk_mul_f32 v[30:31], v[30:31], v[50:51]
	v_lshlrev_b32_e32 v50, 16, v58
	v_and_b32_e32 v51, 0xffff0000, v58
	v_pk_fma_f32 v[32:33], v[18:19], v[30:31], v[32:33]
	v_lshlrev_b32_e32 v54, 16, v63
	v_pk_mul_f32 v[50:51], v[32:33], v[50:51]
	v_lshlrev_b32_e32 v32, 16, v55
	v_and_b32_e32 v33, 0xffff0000, v55
	v_and_b32_e32 v55, 0xffff0000, v63
	v_pk_mul_f32 v[32:33], v[32:33], v[54:55]
	v_lshlrev_b32_e32 v54, 16, v59
	v_and_b32_e32 v55, 0xffff0000, v59
	v_pk_mul_f32 v[58:59], v[16:17], v[44:45]
	v_pk_mul_f32 v[62:63], v[10:11], v[46:47]
	v_pk_fma_f32 v[34:35], v[8:9], v[34:35], v[58:59]
	v_pk_fma_f32 v[36:37], v[2:3], v[36:37], v[62:63]
	v_pk_fma_f32 v[34:35], v[20:21], v[32:33], v[34:35]
	v_pk_mul_f32 v[66:67], v[14:15], v[30:31]
	v_pk_mul_f32 v[58:59], v[34:35], v[54:55]
	v_lshlrev_b32_e32 v34, 16, v56
	v_and_b32_e32 v35, 0xffff0000, v56
	v_lshlrev_b32_e32 v54, 16, v64
	v_and_b32_e32 v55, 0xffff0000, v64
	v_pk_mul_f32 v[34:35], v[34:35], v[54:55]
	v_lshlrev_b32_e32 v54, 16, v60
	v_and_b32_e32 v55, 0xffff0000, v60
	v_pk_fma_f32 v[36:37], v[22:23], v[34:35], v[36:37]
	v_pk_fma_f32 v[40:41], v[6:7], v[40:41], v[66:67]
	v_pk_mul_f32 v[62:63], v[36:37], v[54:55]
	v_lshlrev_b32_e32 v36, 16, v57
	v_and_b32_e32 v37, 0xffff0000, v57
	v_lshlrev_b32_e32 v54, 16, v65
	v_and_b32_e32 v55, 0xffff0000, v65
	v_pk_mul_f32 v[56:57], v[12:13], v[48:49]
	v_pk_mul_f32 v[36:37], v[36:37], v[54:55]
	v_pk_fma_f32 v[38:39], v[4:5], v[38:39], v[56:57]
	v_lshlrev_b32_e32 v54, 16, v61
	v_and_b32_e32 v55, 0xffff0000, v61
	v_pk_fma_f32 v[38:39], v[24:25], v[36:37], v[38:39]
	v_cvt_pk_bf16_f32 v56, v62, v63
	v_pk_mul_f32 v[38:39], v[38:39], v[54:55]
	v_cvt_pk_bf16_f32 v54, v50, v51
	v_cvt_pk_bf16_f32 v55, v58, v59
	v_cvt_pk_bf16_f32 v57, v38, v39
	v_mad_i64_i32 v[38:39], s[10:11], s6, v238, v[28:29]
	s_add_i32 s6, s1, 4
	global_store_dwordx4 v[38:39], v[54:57], off
	v_mad_i64_i32 v[38:39], s[10:11], s6, v233, v[26:27]
	s_waitcnt vmcnt(17)
; __device__ __forceinline__ unsigned cvt_pk_bf16(float lo, float hi) { f32x2_t v = {lo, hi}; bf16x2_t b = __builtin_convertvector(v, bf16x2_t); return __builtin_bit_cast(unsigned, b); }
; __device__ __forceinline__ float bf_lo(unsigned u) { return __uint_as_float(u << 16); }
; __device__ __forceinline__ float bf_hi(unsigned u) { return __uint_as_float(u & 0xffff0000u); }
; __device__ __forceinline__ void prep_items(const Ctx& C, int l, int w0, int nw) {
;     ...
;             for (int tt = 0; tt < 8; ++tt) {
;                 const bf16_t* row = P + (size_t)(tok0 + tt) * PP + lane * 8;
;                 const u32x4 u = *(const u32x4*)row, bb = *(const u32x4*)(row + 512), cc = *(const u32x4*)(row + 1024);
;                 const float c0[8] = {bf_lo(u.x) * bf_lo(cc.x), bf_hi(u.x) * bf_hi(cc.x), bf_lo(u.y) * bf_lo(cc.y), bf_hi(u.y) * bf_hi(cc.y), bf_lo(u.z) * bf_lo(cc.z), bf_hi(u.z) * bf_hi(cc.z), bf_lo(u.w) * bf_lo(cc.w), bf_hi(u.w) * bf_hi(cc.w)};
;                 const float bv[8] = {bf_lo(bb.x), bf_hi(bb.x), bf_lo(bb.y), bf_hi(bb.y), bf_lo(bb.z), bf_hi(bb.z), bf_lo(bb.w), bf_hi(bb.w)};
;                 float o[8];
; #pragma unroll
;                 for (int e = 0; e < 8; ++e) { o[e] = bv[e] * (w[0][e] * c2[e] + w[1][e] * c1[e] + w[2][e] * c0[e]); c2[e] = c1[e]; c1[e] = c0[e]; }
;                 u32x4 ov; ov.x = cvt_pk_bf16(o[0], o[1]); ov.y = cvt_pk_bf16(o[2], o[3]); ov.z = cvt_pk_bf16(o[4], o[5]); ov.w = cvt_pk_bf16(o[6], o[7]);
;                 *(u32x4*)(Y + (size_t)(tok0 + tt) * YP + lane * 8) = ov;
	s_nop 1
	v_mov_b32_e32 v54, v122
	v_mov_b32_e32 v55, v123
	v_mov_b32_e32 v56, v124
	v_mov_b32_e32 v57, v125
	v_mov_b32_e32 v58, v126
	v_mov_b32_e32 v59, v127
	v_mov_b32_e32 v60, v128
	v_mov_b32_e32 v61, v129
	v_mov_b32_e32 v62, v130
	v_mov_b32_e32 v63, v131
	v_mov_b32_e32 v64, v132
	v_mov_b32_e32 v65, v133
	v_lshlrev_b32_e32 v38, 16, v54
	v_and_b32_e32 v39, 0xffff0000, v54
	v_lshlrev_b32_e32 v50, 16, v62
	v_and_b32_e32 v51, 0xffff0000, v62
	v_pk_mul_f32 v[38:39], v[38:39], v[50:51]
	v_lshlrev_b32_e32 v50, 16, v58
	v_and_b32_e32 v51, 0xffff0000, v58
	v_pk_fma_f32 v[40:41], v[18:19], v[38:39], v[40:41]
	v_lshlrev_b32_e32 v54, 16, v63
	v_pk_mul_f32 v[50:51], v[40:41], v[50:51]
	v_lshlrev_b32_e32 v40, 16, v55
	v_and_b32_e32 v41, 0xffff0000, v55
	v_and_b32_e32 v55, 0xffff0000, v63
	v_pk_mul_f32 v[40:41], v[40:41], v[54:55]
	v_lshlrev_b32_e32 v54, 16, v59
	v_and_b32_e32 v55, 0xffff0000, v59
	v_pk_mul_f32 v[58:59], v[16:17], v[32:33]
	v_pk_mul_f32 v[62:63], v[10:11], v[34:35]
	v_pk_fma_f32 v[44:45], v[8:9], v[44:45], v[58:59]
	v_lshlrev_b32_e32 v58, 16, v64
	v_pk_fma_f32 v[44:45], v[20:21], v[40:41], v[44:45]
	v_and_b32_e32 v59, 0xffff0000, v64
	v_pk_mul_f32 v[54:55], v[44:45], v[54:55]
	v_lshlrev_b32_e32 v44, 16, v56
	v_and_b32_e32 v45, 0xffff0000, v56
	v_pk_mul_f32 v[44:45], v[44:45], v[58:59]
	v_pk_fma_f32 v[46:47], v[2:3], v[46:47], v[62:63]
	v_lshlrev_b32_e32 v58, 16, v60
	v_and_b32_e32 v59, 0xffff0000, v60
	v_pk_fma_f32 v[46:47], v[22:23], v[44:45], v[46:47]
	v_lshlrev_b32_e32 v56, 16, v65
	v_pk_mul_f32 v[58:59], v[46:47], v[58:59]
	v_lshlrev_b32_e32 v46, 16, v57
	v_and_b32_e32 v47, 0xffff0000, v57
	v_and_b32_e32 v57, 0xffff0000, v65
	v_pk_mul_f32 v[46:47], v[46:47], v[56:57]
	v_lshlrev_b32_e32 v56, 16, v61
	v_and_b32_e32 v57, 0xffff0000, v61
	v_pk_mul_f32 v[60:61], v[12:13], v[36:37]
	v_pk_mul_f32 v[66:67], v[14:15], v[38:39]
	v_pk_fma_f32 v[48:49], v[4:5], v[48:49], v[60:61]
	v_pk_fma_f32 v[30:31], v[6:7], v[30:31], v[66:67]
	v_pk_fma_f32 v[48:49], v[24:25], v[46:47], v[48:49]
	s_nop 0
	v_pk_mul_f32 v[56:57], v[48:49], v[56:57]
	v_cvt_pk_bf16_f32 v48, v50, v51
	v_cvt_pk_bf16_f32 v49, v54, v55
	v_cvt_pk_bf16_f32 v50, v58, v59
	v_cvt_pk_bf16_f32 v51, v56, v57
	v_mad_i64_i32 v[54:55], s[10:11], s6, v238, v[28:29]
	s_add_i32 s6, s1, 5
	global_store_dwordx4 v[54:55], v[48:51], off
	s_nop 1
	v_mad_i64_i32 v[48:49], s[10:11], s6, v233, v[26:27]
	s_waitcnt vmcnt(15)
	s_nop 1
	v_mov_b32_e32 v54, v134
	v_mov_b32_e32 v55, v135
	v_mov_b32_e32 v56, v136
	v_mov_b32_e32 v57, v137
	v_mov_b32_e32 v58, v138
	v_mov_b32_e32 v59, v139
	v_mov_b32_e32 v60, v140
	v_mov_b32_e32 v61, v141
	v_mov_b32_e32 v62, v142
	v_mov_b32_e32 v63, v143
	v_mov_b32_e32 v64, v144
	v_mov_b32_e32 v65, v145
	v_lshlrev_b32_e32 v48, 16, v54
	v_and_b32_e32 v49, 0xffff0000, v54
	v_lshlrev_b32_e32 v50, 16, v62
	v_and_b32_e32 v51, 0xffff0000, v62
	v_pk_mul_f32 v[48:49], v[48:49], v[50:51]
	v_lshlrev_b32_e32 v50, 16, v58
	v_and_b32_e32 v51, 0xffff0000, v58
	v_pk_fma_f32 v[30:31], v[18:19], v[48:49], v[30:31]
	v_lshlrev_b32_e32 v54, 16, v63
	v_pk_mul_f32 v[50:51], v[30:31], v[50:51]
	v_lshlrev_b32_e32 v30, 16, v55
	v_and_b32_e32 v31, 0xffff0000, v55
	v_and_b32_e32 v55, 0xffff0000, v63
	v_pk_mul_f32 v[30:31], v[30:31], v[54:55]
	v_lshlrev_b32_e32 v54, 16, v59
	v_and_b32_e32 v55, 0xffff0000, v59
	v_pk_mul_f32 v[58:59], v[16:17], v[40:41]
	v_pk_mul_f32 v[62:63], v[10:11], v[44:45]
	v_pk_fma_f32 v[32:33], v[8:9], v[32:33], v[58:59]
	v_pk_fma_f32 v[34:35], v[2:3], v[34:35], v[62:63]
	v_pk_fma_f32 v[32:33], v[20:21], v[30:31], v[32:33]
	v_pk_mul_f32 v[66:67], v[14:15], v[48:49]
	v_pk_mul_f32 v[58:59], v[32:33], v[54:55]
	v_lshlrev_b32_e32 v32, 16, v56
	v_and_b32_e32 v33, 0xffff0000, v56
	v_lshlrev_b32_e32 v54, 16, v64
	v_and_b32_e32 v55, 0xffff0000, v64
	v_pk_mul_f32 v[32:33], v[32:33], v[54:55]
	v_lshlrev_b32_e32 v54, 16, v60
	v_and_b32_e32 v55, 0xffff0000, v60
	v_pk_fma_f32 v[34:35], v[22:23], v[32:33], v[34:35]
	v_pk_fma_f32 v[38:39], v[6:7], v[38:39], v[66:67]
	v_pk_mul_f32 v[62:63], v[34:35], v[54:55]
	v_lshlrev_b32_e32 v34, 16, v57
	v_and_b32_e32 v35, 0xffff0000, v57
	v_lshlrev_b32_e32 v54, 16, v65
	v_and_b32_e32 v55, 0xffff0000, v65
	v_pk_mul_f32 v[56:57], v[12:13], v[46:47]
	v_pk_mul_f32 v[34:35], v[34:35], v[54:55]
	v_pk_fma_f32 v[36:37], v[4:5], v[36:37], v[56:57]
	v_lshlrev_b32_e32 v54, 16, v61
	v_and_b32_e32 v55, 0xffff0000, v61
	v_pk_fma_f32 v[36:37], v[24:25], v[34:35], v[36:37]
	v_cvt_pk_bf16_f32 v56, v62, v63
	v_pk_mul_f32 v[36:37], v[36:37], v[54:55]
	v_cvt_pk_bf16_f32 v54, v50, v51
	v_cvt_pk_bf16_f32 v55, v58, v59
	v_cvt_pk_bf16_f32 v57, v36, v37
	v_mad_i64_i32 v[36:37], s[10:11], s6, v238, v[28:29]
	s_add_i32 s6, s1, 6
	global_store_dwordx4 v[36:37], v[54:57], off
	v_mad_i64_i32 v[36:37], s[10:11], s6, v233, v[26:27]
	s_waitcnt vmcnt(13)
; __device__ __forceinline__ unsigned cvt_pk_bf16(float lo, float hi) { f32x2_t v = {lo, hi}; bf16x2_t b = __builtin_convertvector(v, bf16x2_t); return __builtin_bit_cast(unsigned, b); }
; __device__ __forceinline__ float bf_lo(unsigned u) { return __uint_as_float(u << 16); }
; __device__ __forceinline__ float bf_hi(unsigned u) { return __uint_as_float(u & 0xffff0000u); }
; __device__ __forceinline__ void prep_items(const Ctx& C, int l, int w0, int nw) {
;     ...
;             for (int tt = 0; tt < 8; ++tt) {
;                 const bf16_t* row = P + (size_t)(tok0 + tt) * PP + lane * 8;
;                 const u32x4 u = *(const u32x4*)row, bb = *(const u32x4*)(row + 512), cc = *(const u32x4*)(row + 1024);
;                 const float c0[8] = {bf_lo(u.x) * bf_lo(cc.x), bf_hi(u.x) * bf_hi(cc.x), bf_lo(u.y) * bf_lo(cc.y), bf_hi(u.y) * bf_hi(cc.y), bf_lo(u.z) * bf_lo(cc.z), bf_hi(u.z) * bf_hi(cc.z), bf_lo(u.w) * bf_lo(cc.w), bf_hi(u.w) * bf_hi(cc.w)};
;                 const float bv[8] = {bf_lo(bb.x), bf_hi(bb.x), bf_lo(bb.y), bf_hi(bb.y), bf_lo(bb.z), bf_hi(bb.z), bf_lo(bb.w), bf_hi(bb.w)};
;                 float o[8];
; #pragma unroll
;                 for (int e = 0; e < 8; ++e) { o[e] = bv[e] * (w[0][e] * c2[e] + w[1][e] * c1[e] + w[2][e] * c0[e]); c2[e] = c1[e]; c1[e] = c0[e]; }
;                 u32x4 ov; ov.x = cvt_pk_bf16(o[0], o[1]); ov.y = cvt_pk_bf16(o[2], o[3]); ov.z = cvt_pk_bf16(o[4], o[5]); ov.w = cvt_pk_bf16(o[6], o[7]);
;                 *(u32x4*)(Y + (size_t)(tok0 + tt) * YP + lane * 8) = ov;
	s_nop 1
	v_mov_b32_e32 v54, v146
	v_mov_b32_e32 v55, v147
	v_mov_b32_e32 v56, v148
	v_mov_b32_e32 v57, v149
	v_mov_b32_e32 v58, v150
	v_mov_b32_e32 v59, v151
	v_mov_b32_e32 v60, v152
	v_mov_b32_e32 v61, v153
	v_mov_b32_e32 v62, v154
	v_mov_b32_e32 v63, v155
	v_mov_b32_e32 v64, v156
	v_mov_b32_e32 v65, v157
	v_lshlrev_b32_e32 v36, 16, v54
	v_and_b32_e32 v37, 0xffff0000, v54
	v_lshlrev_b32_e32 v50, 16, v62
	v_and_b32_e32 v51, 0xffff0000, v62
	v_pk_mul_f32 v[36:37], v[36:37], v[50:51]
	v_lshlrev_b32_e32 v50, 16, v58
	v_and_b32_e32 v51, 0xffff0000, v58
	v_pk_fma_f32 v[38:39], v[18:19], v[36:37], v[38:39]
	v_lshlrev_b32_e32 v54, 16, v63
	v_pk_mul_f32 v[50:51], v[38:39], v[50:51]
	v_lshlrev_b32_e32 v38, 16, v55
	v_and_b32_e32 v39, 0xffff0000, v55
	v_and_b32_e32 v55, 0xffff0000, v63
	v_pk_mul_f32 v[38:39], v[38:39], v[54:55]
	v_lshlrev_b32_e32 v54, 16, v59
	v_and_b32_e32 v55, 0xffff0000, v59
	v_pk_mul_f32 v[58:59], v[16:17], v[30:31]
	v_pk_mul_f32 v[62:63], v[10:11], v[32:33]
	v_pk_fma_f32 v[40:41], v[8:9], v[40:41], v[58:59]
	v_pk_fma_f32 v[44:45], v[2:3], v[44:45], v[62:63]
	v_pk_fma_f32 v[40:41], v[20:21], v[38:39], v[40:41]
	v_pk_mul_f32 v[66:67], v[14:15], v[36:37]
	v_pk_mul_f32 v[58:59], v[40:41], v[54:55]
	v_lshlrev_b32_e32 v40, 16, v56
	v_and_b32_e32 v41, 0xffff0000, v56
	v_lshlrev_b32_e32 v54, 16, v64
	v_and_b32_e32 v55, 0xffff0000, v64
	v_pk_mul_f32 v[40:41], v[40:41], v[54:55]
	v_lshlrev_b32_e32 v54, 16, v60
	v_and_b32_e32 v55, 0xffff0000, v60
	v_pk_fma_f32 v[44:45], v[22:23], v[40:41], v[44:45]
	v_pk_fma_f32 v[48:49], v[6:7], v[48:49], v[66:67]
	v_pk_mul_f32 v[62:63], v[44:45], v[54:55]
	v_lshlrev_b32_e32 v44, 16, v57
	v_and_b32_e32 v45, 0xffff0000, v57
	v_lshlrev_b32_e32 v54, 16, v65
	v_and_b32_e32 v55, 0xffff0000, v65
	v_pk_mul_f32 v[56:57], v[12:13], v[34:35]
	v_pk_mul_f32 v[44:45], v[44:45], v[54:55]
	v_pk_fma_f32 v[46:47], v[4:5], v[46:47], v[56:57]
	v_lshlrev_b32_e32 v54, 16, v61
	v_and_b32_e32 v55, 0xffff0000, v61
	v_pk_fma_f32 v[46:47], v[24:25], v[44:45], v[46:47]
	v_cvt_pk_bf16_f32 v56, v62, v63
	v_pk_mul_f32 v[46:47], v[46:47], v[54:55]
	v_cvt_pk_bf16_f32 v54, v50, v51
	v_cvt_pk_bf16_f32 v55, v58, v59
	v_cvt_pk_bf16_f32 v57, v46, v47
	v_mad_i64_i32 v[46:47], s[10:11], s6, v238, v[28:29]
	s_add_i32 s6, s1, 7
	global_store_dwordx4 v[46:47], v[54:57], off
	v_mad_i64_i32 v[46:47], s[10:11], s6, v233, v[26:27]
	s_waitcnt vmcnt(11)
	s_nop 1
	v_mov_b32_e32 v54, v158
	v_mov_b32_e32 v55, v159
	v_mov_b32_e32 v56, v160
	v_mov_b32_e32 v57, v161
	v_mov_b32_e32 v58, v162
	v_mov_b32_e32 v59, v163
	v_mov_b32_e32 v60, v164
	v_mov_b32_e32 v61, v165
	v_mov_b32_e32 v62, v166
	v_mov_b32_e32 v63, v167
	v_mov_b32_e32 v64, v168
	v_mov_b32_e32 v65, v169
	v_lshlrev_b32_e32 v46, 16, v54
	v_and_b32_e32 v47, 0xffff0000, v54
	v_lshlrev_b32_e32 v50, 16, v62
	v_and_b32_e32 v51, 0xffff0000, v62
	v_pk_mul_f32 v[46:47], v[46:47], v[50:51]
	v_lshlrev_b32_e32 v50, 16, v58
	v_and_b32_e32 v51, 0xffff0000, v58
	v_pk_fma_f32 v[48:49], v[18:19], v[46:47], v[48:49]
	v_lshlrev_b32_e32 v54, 16, v63
	v_pk_mul_f32 v[50:51], v[48:49], v[50:51]
	v_lshlrev_b32_e32 v48, 16, v55
	v_and_b32_e32 v49, 0xffff0000, v55
	v_and_b32_e32 v55, 0xffff0000, v63
	v_pk_mul_f32 v[48:49], v[48:49], v[54:55]
	v_lshlrev_b32_e32 v54, 16, v59
	v_and_b32_e32 v55, 0xffff0000, v59
	v_pk_mul_f32 v[58:59], v[16:17], v[38:39]
	v_pk_mul_f32 v[62:63], v[10:11], v[40:41]
	v_pk_fma_f32 v[30:31], v[8:9], v[30:31], v[58:59]
	v_pk_fma_f32 v[32:33], v[2:3], v[32:33], v[62:63]
	v_pk_fma_f32 v[30:31], v[20:21], v[48:49], v[30:31]
	v_pk_mul_f32 v[66:67], v[14:15], v[46:47]
	v_pk_mul_f32 v[58:59], v[30:31], v[54:55]
	v_lshlrev_b32_e32 v30, 16, v56
	v_and_b32_e32 v31, 0xffff0000, v56
	v_lshlrev_b32_e32 v54, 16, v64
	v_and_b32_e32 v55, 0xffff0000, v64
	v_pk_mul_f32 v[30:31], v[30:31], v[54:55]
	v_lshlrev_b32_e32 v54, 16, v60
	v_and_b32_e32 v55, 0xffff0000, v60
	v_pk_fma_f32 v[32:33], v[22:23], v[30:31], v[32:33]
	v_pk_fma_f32 v[36:37], v[6:7], v[36:37], v[66:67]
	v_pk_mul_f32 v[62:63], v[32:33], v[54:55]
	v_lshlrev_b32_e32 v32, 16, v57
	v_and_b32_e32 v33, 0xffff0000, v57
	v_lshlrev_b32_e32 v54, 16, v65
	v_and_b32_e32 v55, 0xffff0000, v65
	v_pk_mul_f32 v[56:57], v[12:13], v[44:45]
	v_pk_mul_f32 v[32:33], v[32:33], v[54:55]
	v_pk_fma_f32 v[34:35], v[4:5], v[34:35], v[56:57]
	v_lshlrev_b32_e32 v54, 16, v61
	v_and_b32_e32 v55, 0xffff0000, v61
	v_pk_fma_f32 v[34:35], v[24:25], v[32:33], v[34:35]
	v_cvt_pk_bf16_f32 v56, v62, v63
	v_pk_mul_f32 v[34:35], v[34:35], v[54:55]
	v_cvt_pk_bf16_f32 v54, v50, v51
	v_cvt_pk_bf16_f32 v55, v58, v59
	v_cvt_pk_bf16_f32 v57, v34, v35
	v_mad_i64_i32 v[34:35], s[10:11], s6, v238, v[28:29]
	s_add_i32 s6, s1, 8
	global_store_dwordx4 v[34:35], v[54:57], off
	v_mad_i64_i32 v[34:35], s[10:11], s6, v233, v[26:27]
	s_waitcnt vmcnt(9)
; __device__ __forceinline__ unsigned cvt_pk_bf16(float lo, float hi) { f32x2_t v = {lo, hi}; bf16x2_t b = __builtin_convertvector(v, bf16x2_t); return __builtin_bit_cast(unsigned, b); }
; __device__ __forceinline__ float bf_lo(unsigned u) { return __uint_as_float(u << 16); }
; __device__ __forceinline__ float bf_hi(unsigned u) { return __uint_as_float(u & 0xffff0000u); }
; __device__ __forceinline__ void prep_items(const Ctx& C, int l, int w0, int nw) {
;     ...
;             for (int tt = 0; tt < 8; ++tt) {
;                 const bf16_t* row = P + (size_t)(tok0 + tt) * PP + lane * 8;
;                 const u32x4 u = *(const u32x4*)row, bb = *(const u32x4*)(row + 512), cc = *(const u32x4*)(row + 1024);
;                 const float c0[8] = {bf_lo(u.x) * bf_lo(cc.x), bf_hi(u.x) * bf_hi(cc.x), bf_lo(u.y) * bf_lo(cc.y), bf_hi(u.y) * bf_hi(cc.y), bf_lo(u.z) * bf_lo(cc.z), bf_hi(u.z) * bf_hi(cc.z), bf_lo(u.w) * bf_lo(cc.w), bf_hi(u.w) * bf_hi(cc.w)};
;                 const float bv[8] = {bf_lo(bb.x), bf_hi(bb.x), bf_lo(bb.y), bf_hi(bb.y), bf_lo(bb.z), bf_hi(bb.z), bf_lo(bb.w), bf_hi(bb.w)};
;                 float o[8];
; #pragma unroll
;                 for (int e = 0; e < 8; ++e) { o[e] = bv[e] * (w[0][e] * c2[e] + w[1][e] * c1[e] + w[2][e] * c0[e]); c2[e] = c1[e]; c1[e] = c0[e]; }
;                 u32x4 ov; ov.x = cvt_pk_bf16(o[0], o[1]); ov.y = cvt_pk_bf16(o[2], o[3]); ov.z = cvt_pk_bf16(o[4], o[5]); ov.w = cvt_pk_bf16(o[6], o[7]);
;                 *(u32x4*)(Y + (size_t)(tok0 + tt) * YP + lane * 8) = ov;
;             }
;         }
	s_nop 1
	v_mov_b32_e32 v54, v170
	v_mov_b32_e32 v55, v171
	v_mov_b32_e32 v56, v172
	v_mov_b32_e32 v57, v173
	v_mov_b32_e32 v58, v174
	v_mov_b32_e32 v59, v175
	v_mov_b32_e32 v60, v176
	v_mov_b32_e32 v61, v177
	v_mov_b32_e32 v62, v178
	v_mov_b32_e32 v63, v179
	v_mov_b32_e32 v64, v180
	v_mov_b32_e32 v65, v181
	v_lshlrev_b32_e32 v34, 16, v54
	v_and_b32_e32 v35, 0xffff0000, v54
	v_lshlrev_b32_e32 v50, 16, v62
	v_and_b32_e32 v51, 0xffff0000, v62
	v_pk_mul_f32 v[34:35], v[34:35], v[50:51]
	v_lshlrev_b32_e32 v50, 16, v58
	v_and_b32_e32 v51, 0xffff0000, v58
	v_pk_fma_f32 v[36:37], v[18:19], v[34:35], v[36:37]
	v_lshlrev_b32_e32 v54, 16, v63
	v_pk_mul_f32 v[50:51], v[36:37], v[50:51]
	v_lshlrev_b32_e32 v36, 16, v55
	v_and_b32_e32 v37, 0xffff0000, v55
	v_and_b32_e32 v55, 0xffff0000, v63
	v_pk_mul_f32 v[36:37], v[36:37], v[54:55]
	v_lshlrev_b32_e32 v54, 16, v59
	v_and_b32_e32 v55, 0xffff0000, v59
	v_pk_mul_f32 v[58:59], v[16:17], v[48:49]
	v_pk_mul_f32 v[62:63], v[10:11], v[30:31]
	v_pk_fma_f32 v[38:39], v[8:9], v[38:39], v[58:59]
	v_pk_fma_f32 v[40:41], v[2:3], v[40:41], v[62:63]
	v_pk_fma_f32 v[38:39], v[20:21], v[36:37], v[38:39]
	v_pk_mul_f32 v[34:35], v[14:15], v[34:35]
	v_pk_mul_f32 v[58:59], v[38:39], v[54:55]
	v_lshlrev_b32_e32 v38, 16, v56
	v_and_b32_e32 v39, 0xffff0000, v56
	v_lshlrev_b32_e32 v54, 16, v64
	v_and_b32_e32 v55, 0xffff0000, v64
	v_pk_mul_f32 v[38:39], v[38:39], v[54:55]
	v_lshlrev_b32_e32 v54, 16, v60
	v_and_b32_e32 v55, 0xffff0000, v60
	v_pk_fma_f32 v[40:41], v[22:23], v[38:39], v[40:41]
	v_pk_fma_f32 v[34:35], v[6:7], v[46:47], v[34:35]
	v_pk_mul_f32 v[62:63], v[40:41], v[54:55]
	v_lshlrev_b32_e32 v40, 16, v57
	v_and_b32_e32 v41, 0xffff0000, v57
	v_lshlrev_b32_e32 v54, 16, v65
	v_and_b32_e32 v55, 0xffff0000, v65
	v_pk_mul_f32 v[56:57], v[12:13], v[32:33]
	v_pk_mul_f32 v[40:41], v[40:41], v[54:55]
	v_pk_fma_f32 v[44:45], v[4:5], v[44:45], v[56:57]
	v_lshlrev_b32_e32 v54, 16, v61
	v_and_b32_e32 v55, 0xffff0000, v61
	v_pk_fma_f32 v[44:45], v[24:25], v[40:41], v[44:45]
	v_cvt_pk_bf16_f32 v56, v62, v63
	v_pk_mul_f32 v[44:45], v[44:45], v[54:55]
	v_cvt_pk_bf16_f32 v54, v50, v51
	v_cvt_pk_bf16_f32 v55, v58, v59
	v_cvt_pk_bf16_f32 v57, v44, v45
	v_mad_i64_i32 v[44:45], s[10:11], s6, v238, v[28:29]
	s_add_i32 s6, s1, 9
	global_store_dwordx4 v[44:45], v[54:57], off
	v_mad_i64_i32 v[44:45], s[10:11], s6, v233, v[26:27]
	s_waitcnt vmcnt(7)
	s_nop 1
	v_mov_b32_e32 v54, v182
	v_mov_b32_e32 v55, v183
	v_mov_b32_e32 v56, v184
	v_mov_b32_e32 v57, v185
	v_mov_b32_e32 v58, v186
	v_mov_b32_e32 v59, v187
	v_mov_b32_e32 v60, v188
	v_mov_b32_e32 v61, v189
	v_mov_b32_e32 v62, v190
	v_mov_b32_e32 v63, v191
	v_mov_b32_e32 v64, v192
	v_mov_b32_e32 v65, v193
	v_pk_mul_f32 v[36:37], v[16:17], v[36:37]
	v_pk_mul_f32 v[38:39], v[10:11], v[38:39]
	v_pk_fma_f32 v[36:37], v[8:9], v[48:49], v[36:37]
	v_pk_fma_f32 v[30:31], v[2:3], v[30:31], v[38:39]
	v_pk_mul_f32 v[40:41], v[12:13], v[40:41]
	s_add_i32 s1, s1, s9
	v_pk_fma_f32 v[32:33], v[4:5], v[32:33], v[40:41]
	s_cmpk_gt_i32 s3, 0xfff
	v_lshlrev_b32_e32 v44, 16, v54
	v_and_b32_e32 v45, 0xffff0000, v54
	v_lshlrev_b32_e32 v50, 16, v62
	v_and_b32_e32 v51, 0xffff0000, v62
	v_pk_mul_f32 v[44:45], v[44:45], v[50:51]
	v_lshlrev_b32_e32 v46, 16, v63
	v_pk_fma_f32 v[34:35], v[18:19], v[44:45], v[34:35]
	v_lshlrev_b32_e32 v44, 16, v55
	v_and_b32_e32 v45, 0xffff0000, v55
	v_and_b32_e32 v47, 0xffff0000, v63
	v_pk_mul_f32 v[44:45], v[44:45], v[46:47]
	v_lshlrev_b32_e32 v46, 16, v59
	v_and_b32_e32 v47, 0xffff0000, v59
	v_pk_fma_f32 v[36:37], v[20:21], v[44:45], v[36:37]
	v_lshlrev_b32_e32 v44, 16, v56
	v_pk_mul_f32 v[36:37], v[36:37], v[46:47]
	v_and_b32_e32 v45, 0xffff0000, v56
	v_lshlrev_b32_e32 v46, 16, v64
	v_and_b32_e32 v47, 0xffff0000, v64
	v_pk_mul_f32 v[44:45], v[44:45], v[46:47]
	v_lshlrev_b32_e32 v46, 16, v60
	v_and_b32_e32 v47, 0xffff0000, v60
	v_pk_fma_f32 v[30:31], v[22:23], v[44:45], v[30:31]
	v_lshlrev_b32_e32 v44, 16, v65
	v_pk_mul_f32 v[38:39], v[30:31], v[46:47]
	v_lshlrev_b32_e32 v30, 16, v57
	v_and_b32_e32 v31, 0xffff0000, v57
	v_and_b32_e32 v45, 0xffff0000, v65
	v_pk_mul_f32 v[30:31], v[30:31], v[44:45]
	v_lshlrev_b32_e32 v50, 16, v58
	v_and_b32_e32 v51, 0xffff0000, v58
	v_lshlrev_b32_e32 v44, 16, v61
	v_and_b32_e32 v45, 0xffff0000, v61
	v_pk_fma_f32 v[30:31], v[24:25], v[30:31], v[32:33]
	v_pk_mul_f32 v[34:35], v[34:35], v[50:51]
	v_pk_mul_f32 v[40:41], v[30:31], v[44:45]
	v_cvt_pk_bf16_f32 v30, v34, v35
	v_cvt_pk_bf16_f32 v31, v36, v37
	v_cvt_pk_bf16_f32 v32, v38, v39
	v_cvt_pk_bf16_f32 v33, v40, v41
	v_mad_i64_i32 v[34:35], s[10:11], s6, v238, v[28:29]
	global_store_dwordx4 v[34:35], v[30:33], off
	s_cbranch_scc1 .LBB0_477
; __device__ __forceinline__ float bf_lo(unsigned u) { return __uint_as_float(u << 16); }
; __device__ __forceinline__ float bf_hi(unsigned u) { return __uint_as_float(u & 0xffff0000u); }
; __device__ __forceinline__ void prep_items(const Ctx& C, int l, int w0, int nw) {
;     ...
;         for (int it = w0; it < T_ / 8; it += nw) {
;             const int tok0 = it * 8, s0 = tok0 & (S_ - 1);
;             float c1[8], c2[8];
; #pragma unroll
;             for (int e = 0; e < 8; ++e) { c1[e] = 0.f; c2[e] = 0.f; }
;             if (s0 > 0) {
; #pragma unroll
;     ...
;                     const bf16_t* row = P + (size_t)(tok0 - back) * PP + lane * 8;
;                     const u32x4 u = *(const u32x4*)row, cc = *(const u32x4*)(row + 1024);
;                     float t[8] = {bf_lo(u.x) * bf_lo(cc.x), bf_hi(u.x) * bf_hi(cc.x), bf_lo(u.y) * bf_lo(cc.y), bf_hi(u.y) * bf_hi(cc.y), bf_lo(u.z) * bf_lo(cc.z), bf_hi(u.z) * bf_hi(cc.z), bf_lo(u.w) * bf_lo(cc.w), bf_hi(u.w) * bf_hi(cc.w)};
; #pragma unroll
;                     for (int e = 0; e < 8; ++e) { if (back == 2) c2[e] = t[e]; else c1[e] = t[e]; }
;                 }
;             }
; #pragma unroll
;             for (int tt = 0; tt < 8; ++tt) {
.LBB0_475:
	s_add_i32 s6, s1, 2
	v_mad_i64_i32 v[212:213], s[10:11], s6, v233, v[26:27]
	global_load_dwordx4 v[98:101], v[212:213], off
	global_load_dwordx4 v[102:105], v[212:213], off offset:1024
	global_load_dwordx4 v[106:109], v[212:213], off offset:2048
	s_add_i32 s6, s1, 3
	v_mad_i64_i32 v[212:213], s[10:11], s6, v233, v[26:27]
	global_load_dwordx4 v[110:113], v[212:213], off
	global_load_dwordx4 v[114:117], v[212:213], off offset:1024
	global_load_dwordx4 v[118:121], v[212:213], off offset:2048
	s_add_i32 s6, s1, 4
	v_mad_i64_i32 v[212:213], s[10:11], s6, v233, v[26:27]
	global_load_dwordx4 v[122:125], v[212:213], off
	global_load_dwordx4 v[126:129], v[212:213], off offset:1024
	global_load_dwordx4 v[130:133], v[212:213], off offset:2048
	s_add_i32 s6, s1, 5
	v_mad_i64_i32 v[212:213], s[10:11], s6, v233, v[26:27]
	global_load_dwordx4 v[134:137], v[212:213], off
	global_load_dwordx4 v[138:141], v[212:213], off offset:1024
	global_load_dwordx4 v[142:145], v[212:213], off offset:2048
	s_add_i32 s6, s1, 6
	v_mad_i64_i32 v[212:213], s[10:11], s6, v233, v[26:27]
	global_load_dwordx4 v[146:149], v[212:213], off
	global_load_dwordx4 v[150:153], v[212:213], off offset:1024
	global_load_dwordx4 v[154:157], v[212:213], off offset:2048
	s_add_i32 s6, s1, 7
	v_mad_i64_i32 v[212:213], s[10:11], s6, v233, v[26:27]
	global_load_dwordx4 v[158:161], v[212:213], off
	global_load_dwordx4 v[162:165], v[212:213], off offset:1024
	global_load_dwordx4 v[166:169], v[212:213], off offset:2048
	s_add_i32 s6, s1, 8
	v_mad_i64_i32 v[212:213], s[10:11], s6, v233, v[26:27]
	global_load_dwordx4 v[170:173], v[212:213], off
	global_load_dwordx4 v[174:177], v[212:213], off offset:1024
	global_load_dwordx4 v[178:181], v[212:213], off offset:2048
	s_add_i32 s6, s1, 9
	v_mad_i64_i32 v[212:213], s[10:11], s6, v233, v[26:27]
	global_load_dwordx4 v[182:185], v[212:213], off
	global_load_dwordx4 v[186:189], v[212:213], off offset:1024
	global_load_dwordx4 v[190:193], v[212:213], off offset:2048
	s_and_b32 s6, s3, 0x7ff
	s_cmp_eq_u32 s6, 0
	s_cbranch_scc0 .LBB0_473
	v_mov_b32_e32 v38, 0
	v_mov_b32_e32 v39, v38
	v_mov_b32_e32 v36, v38
	v_mov_b32_e32 v37, v38
	v_mov_b32_e32 v34, v38
	v_mov_b32_e32 v35, v38
	v_mov_b32_e32 v32, v38
	v_mov_b32_e32 v33, v38
	v_mov_b32_e32 v50, v38
	v_mov_b32_e32 v51, v38
	v_mov_b32_e32 v48, v38
	v_mov_b32_e32 v49, v38
	v_mov_b32_e32 v46, v38
	v_mov_b32_e32 v47, v38
	v_mov_b32_e32 v44, v38
	v_mov_b32_e32 v45, v38
	s_branch .LBB0_474

; __device__ __forceinline__ float bf_lo(unsigned u) { return __uint_as_float(u << 16); }
; __device__ __forceinline__ float bf_hi(unsigned u) { return __uint_as_float(u & 0xffff0000u); }
; __device__ __forceinline__ void norm_phase(const Ctx& C, int w0, int nw, const float* xin, float* xout, const bf16_t* y, bf16_t* h, const float* gpost, const float* gpre, float coef) {
;     for (int m0 = w0; m0 < T_; m0 += 2 * nw) {
;         f32x4 xv[2][4]; u32x2 yw[2][4];
; #pragma unroll
;         for (int r = 0; r < 2; ++r) { const int m = (m0 + r * nw < T_) ? m0 + r * nw : m0; const f32x4* xr = (const f32x4*)(xin + (size_t)m * DM) + C.lane; const u32x2* yr = (const u32x2*)(y + (size_t)m * DM) + C.lane;
; #pragma unroll
;             for (int j = 0; j < 4; ++j) { xv[r][j] = xr[64 * j]; yw[r][j] = yr[64 * j]; } }
; #pragma unroll
;         for (int r = 0; r < 2; ++r) {
;             const int m = m0 + r * nw; if (m >= T_) break;
;             f32x4 yv[4]; float s = 0.f;
; #pragma unroll
;             for (int j = 0; j < 4; ++j) { const u32x2 w = yw[r][j]; yv[j] = (f32x4){bf_lo(w.x), bf_hi(w.x), bf_lo(w.y), bf_hi(w.y)};
;                 s += (yv[j].x * yv[j].x + yv[j].y * yv[j].y) + (yv[j].z * yv[j].z + yv[j].w * yv[j].w); }
;             const float rs = rsqrtf(wave_sum(s) * (1.f / DM) + EPS) * coef; float s2 = 0.f;
;             f32x4* xo = (f32x4*)(xout + (size_t)m * DM) + C.lane;
; #pragma unroll
;             for (int j = 0; j < 4; ++j) { const f32x4 gg = ((const f32x4*)gpost)[C.lane + 64 * j]; xv[r][j] = xv[r][j] + yv[j] * gg * rs; xo[64 * j] = xv[r][j];
.LBB0_1402:
	s_mov_b32 s10, s0
	global_load_dwordx4 v[100:103], v[40:41], off
	global_load_dwordx4 v[104:107], v[40:41], off offset:1024
	global_load_dwordx4 v[108:111], v[40:41], off offset:2048
	global_load_dwordx4 v[112:115], v[40:41], off offset:3072
	s_and_b64 vcc, exec, s[28:29]
	s_cbranch_vccz .Ln14_loop
	global_load_dwordx4 v[116:119], v[42:43], off
	global_load_dwordx4 v[120:123], v[42:43], off offset:1024
	global_load_dwordx4 v[124:127], v[42:43], off offset:2048
	global_load_dwordx4 v[128:131], v[42:43], off offset:3072
.Ln14_loop:
	s_ashr_i32 s11, s10, 31
	s_add_i32 s12, s10, s70
	s_cmp_lt_i32 s12, 0x8000
	s_cselect_b64 s[18:19], -1, 0
	s_cselect_b32 s0, s12, s10
	s_ashr_i32 s1, s0, 31
	s_lshl_b64 s[2:3], s[10:11], 11
	v_lshl_add_u64 v[4:5], v[38:39], 0, s[2:3]
	v_lshl_add_u64 v[10:11], v[38:39], 0, s[2:3]
	s_lshl_b64 s[2:3], s[10:11], 12
	v_lshl_add_u64 v[2:3], v[36:37], 0, s[2:3]
	v_lshl_add_u64 v[28:29], v[36:37], 0, s[2:3]
	s_lshl_b64 s[2:3], s[0:1], 11
	v_lshl_add_u64 v[8:9], v[38:39], 0, s[2:3]
	v_lshl_add_u64 v[12:13], v[38:39], 0, s[2:3]
	s_lshl_b64 s[2:3], s[0:1], 12
	v_lshl_add_u64 v[6:7], v[36:37], 0, s[2:3]
	v_lshl_add_u64 v[30:31], v[36:37], 0, s[2:3]
	global_load_dwordx2 v[160:161], v[4:5], off
	global_load_dwordx2 v[162:163], v[4:5], off offset:512
	global_load_dwordx2 v[164:165], v[4:5], off offset:1024
	global_load_dwordx2 v[166:167], v[4:5], off offset:1536
	global_load_dwordx4 v[144:147], v[2:3], off
	global_load_dwordx4 v[148:151], v[2:3], off offset:1024
	global_load_dwordx4 v[152:155], v[2:3], off offset:2048
	global_load_dwordx4 v[156:159], v[2:3], off offset:3072
	global_load_dwordx2 v[184:185], v[8:9], off
	global_load_dwordx2 v[186:187], v[8:9], off offset:512
	global_load_dwordx2 v[188:189], v[8:9], off offset:1024
	global_load_dwordx2 v[190:191], v[8:9], off offset:1536
	global_load_dwordx4 v[168:171], v[6:7], off
	global_load_dwordx4 v[172:175], v[6:7], off offset:1024
	global_load_dwordx4 v[176:179], v[6:7], off offset:2048
	global_load_dwordx4 v[180:183], v[6:7], off offset:3072
	s_waitcnt vmcnt(12)
	v_lshlrev_b32_e32 v44, 16, v160
	v_and_b32_e32 v45, 0xffff0000, v160
	v_lshlrev_b32_e32 v46, 16, v161
	v_and_b32_e32 v47, 0xffff0000, v161
	v_lshlrev_b32_e32 v48, 16, v162
	v_and_b32_e32 v49, 0xffff0000, v162
	v_lshlrev_b32_e32 v50, 16, v163
	v_and_b32_e32 v51, 0xffff0000, v163
	v_lshlrev_b32_e32 v52, 16, v164
	v_and_b32_e32 v53, 0xffff0000, v164
	v_lshlrev_b32_e32 v54, 16, v165
	v_and_b32_e32 v55, 0xffff0000, v165
	v_lshlrev_b32_e32 v60, 16, v166
	v_and_b32_e32 v61, 0xffff0000, v166
	v_lshlrev_b32_e32 v62, 16, v167
	v_and_b32_e32 v63, 0xffff0000, v167
	v_mul_f32_e32 v14, v45, v45
	v_mul_f32_e32 v15, v47, v47
	v_mul_f32_e32 v16, v49, v49
	v_mul_f32_e32 v17, v51, v51
	v_mul_f32_e32 v18, v53, v53
	v_mul_f32_e32 v19, v55, v55
	v_mul_f32_e32 v20, v61, v61
	v_mul_f32_e32 v21, v63, v63
	v_fmac_f32_e32 v14, v44, v44
	v_fmac_f32_e32 v15, v46, v46
	v_fmac_f32_e32 v16, v48, v48
	v_fmac_f32_e32 v17, v50, v50
	v_fmac_f32_e32 v18, v52, v52
	v_fmac_f32_e32 v19, v54, v54
	v_fmac_f32_e32 v20, v60, v60
	v_fmac_f32_e32 v21, v62, v62
	v_add_f32_e32 v14, v14, v15
	v_add_f32_e32 v16, v16, v17
	v_add_f32_e32 v18, v18, v19
	v_add_f32_e32 v20, v20, v21
	v_add_f32_e32 v22, v14, v16
	v_add_f32_e32 v22, v18, v22
	v_add_f32_e32 v22, v20, v22
	s_nop 1
	v_add_f32_dpp v22, v22, v22 quad_perm:[1,0,3,2] row_mask:0xf bank_mask:0xf bound_ctrl:1
	s_nop 1
	v_add_f32_dpp v22, v22, v22 quad_perm:[2,3,0,1] row_mask:0xf bank_mask:0xf bound_ctrl:1
	s_nop 1
	v_add_f32_dpp v22, v22, v22 row_half_mirror row_mask:0xf bank_mask:0xf bound_ctrl:1
	s_nop 1
	v_add_f32_dpp v22, v22, v22 row_mirror row_mask:0xf bank_mask:0xf bound_ctrl:1
	v_mov_b32_e32 v23, v22
	s_nop 1
	v_permlane16_swap_b32_e32 v22, v23
	v_add_f32_e32 v22, v22, v23
	v_mov_b32_e32 v23, v22
	s_nop 1
	v_permlane32_swap_b32_e32 v22, v23
	v_add_f32_e32 v22, v22, v23
	v_fmamk_f32 v22, v22, 0x3a800000, v248
	v_mul_f32_e32 v23, 0x4b800000, v22
	v_cmp_gt_f32_e32 vcc, s64, v22
	s_nop 1
	v_cndmask_b32_e32 v22, v22, v23, vcc
	v_rsq_f32_e32 v22, v22
	s_nop 0
	v_mul_f32_e32 v23, 0x45800000, v22
	v_cndmask_b32_e32 v22, v22, v23, vcc
	v_mul_f32_e32 v22, 0.5, v22
	s_waitcnt vmcnt(8)
	v_mul_f32_e32 v24, v44, v100
	v_mul_f32_e32 v25, v45, v101
	v_mul_f32_e32 v26, v46, v102
	v_mul_f32_e32 v27, v47, v103
	v_fmac_f32_e32 v144, v24, v22
	v_fmac_f32_e32 v145, v25, v22
	v_fmac_f32_e32 v146, v26, v22
	v_fmac_f32_e32 v147, v27, v22
	v_mul_f32_e32 v24, v48, v104
	v_mul_f32_e32 v25, v49, v105
	v_mul_f32_e32 v26, v50, v106
	v_mul_f32_e32 v27, v51, v107
	v_fmac_f32_e32 v148, v24, v22
	v_fmac_f32_e32 v149, v25, v22
	v_fmac_f32_e32 v150, v26, v22
	v_fmac_f32_e32 v151, v27, v22
	v_mul_f32_e32 v24, v52, v108
	v_mul_f32_e32 v25, v53, v109
	v_mul_f32_e32 v26, v54, v110
	v_mul_f32_e32 v27, v55, v111
	v_fmac_f32_e32 v152, v24, v22
	v_fmac_f32_e32 v153, v25, v22
	v_fmac_f32_e32 v154, v26, v22
	v_fmac_f32_e32 v155, v27, v22
	v_mul_f32_e32 v24, v60, v112
	v_mul_f32_e32 v25, v61, v113
	v_mul_f32_e32 v26, v62, v114
	v_mul_f32_e32 v27, v63, v115
	v_fmac_f32_e32 v156, v24, v22
	v_fmac_f32_e32 v157, v25, v22
	v_fmac_f32_e32 v158, v26, v22
	v_fmac_f32_e32 v159, v27, v22
	s_and_b64 vcc, exec, s[28:29]
	s_cbranch_vccz .Ln14_noh_A
; __device__ __forceinline__ unsigned cvt_pk_bf16(float lo, float hi) { f32x2_t v = {lo, hi}; bf16x2_t b = __builtin_convertvector(v, bf16x2_t); return __builtin_bit_cast(unsigned, b); }
; __device__ __forceinline__ float bf_lo(unsigned u) { return __uint_as_float(u << 16); }
; __device__ __forceinline__ float bf_hi(unsigned u) { return __uint_as_float(u & 0xffff0000u); }
; __device__ __forceinline__ void norm_phase(const Ctx& C, int w0, int nw, const float* xin, float* xout, const bf16_t* y, bf16_t* h, const float* gpost, const float* gpre, float coef) {
;     ...
;         for (int r = 0; r < 2; ++r) {
;             const int m = m0 + r * nw; if (m >= T_) break;
;             f32x4 yv[4]; float s = 0.f;
; #pragma unroll
;             for (int j = 0; j < 4; ++j) { const u32x2 w = yw[r][j]; yv[j] = (f32x4){bf_lo(w.x), bf_hi(w.x), bf_lo(w.y), bf_hi(w.y)};
;                 s += (yv[j].x * yv[j].x + yv[j].y * yv[j].y) + (yv[j].z * yv[j].z + yv[j].w * yv[j].w); }
;             const float rs = rsqrtf(wave_sum(s) * (1.f / DM) + EPS) * coef; float s2 = 0.f;
;             f32x4* xo = (f32x4*)(xout + (size_t)m * DM) + C.lane;
; #pragma unroll
;             for (int j = 0; j < 4; ++j) { const f32x4 gg = ((const f32x4*)gpost)[C.lane + 64 * j]; xv[r][j] = xv[r][j] + yv[j] * gg * rs; xo[64 * j] = xv[r][j];
;                 s2 += (xv[r][j].x * xv[r][j].x + xv[r][j].y * xv[r][j].y) + (xv[r][j].z * xv[r][j].z + xv[r][j].w * xv[r][j].w); }
;             if (gpre) {
;                 const float r2 = rsqrtf(wave_sum(s2) * (1.f / DM) + EPS);
;                 u32x2* o = (u32x2*)(h + (size_t)m * DM) + C.lane;
; #pragma unroll
;                 for (int j = 0; j < 4; ++j) { const f32x4 gg = ((const f32x4*)gpre)[C.lane + 64 * j]; u32x2 w; w.x = cvt_pk_bf16(xv[r][j].x * r2 * gg.x, xv[r][j].y * r2 * gg.y); w.y = cvt_pk_bf16(xv[r][j].z * r2 * gg.z, xv[r][j].w * r2 * gg.w); o[64 * j] = w; }
;             }
	v_mul_f32_e32 v14, v145, v145
	v_mul_f32_e32 v15, v147, v147
	v_mul_f32_e32 v16, v149, v149
	v_mul_f32_e32 v17, v151, v151
	v_mul_f32_e32 v18, v153, v153
	v_mul_f32_e32 v19, v155, v155
	v_mul_f32_e32 v20, v157, v157
	v_mul_f32_e32 v21, v159, v159
	v_fmac_f32_e32 v14, v144, v144
	v_fmac_f32_e32 v15, v146, v146
	v_fmac_f32_e32 v16, v148, v148
	v_fmac_f32_e32 v17, v150, v150
	v_fmac_f32_e32 v18, v152, v152
	v_fmac_f32_e32 v19, v154, v154
	v_fmac_f32_e32 v20, v156, v156
	v_fmac_f32_e32 v21, v158, v158
	v_add_f32_e32 v14, v14, v15
	v_add_f32_e32 v16, v16, v17
	v_add_f32_e32 v18, v18, v19
	v_add_f32_e32 v20, v20, v21
	v_add_f32_e32 v22, v14, v16
	v_add_f32_e32 v22, v18, v22
	v_add_f32_e32 v22, v20, v22
	s_nop 1
	v_add_f32_dpp v22, v22, v22 quad_perm:[1,0,3,2] row_mask:0xf bank_mask:0xf bound_ctrl:1
	s_nop 1
	v_add_f32_dpp v22, v22, v22 quad_perm:[2,3,0,1] row_mask:0xf bank_mask:0xf bound_ctrl:1
	s_nop 1
	v_add_f32_dpp v22, v22, v22 row_half_mirror row_mask:0xf bank_mask:0xf bound_ctrl:1
	s_nop 1
	v_add_f32_dpp v22, v22, v22 row_mirror row_mask:0xf bank_mask:0xf bound_ctrl:1
	v_mov_b32_e32 v23, v22
	s_nop 1
	v_permlane16_swap_b32_e32 v22, v23
	v_add_f32_e32 v22, v22, v23
	v_mov_b32_e32 v23, v22
	s_nop 1
	v_permlane32_swap_b32_e32 v22, v23
	v_add_f32_e32 v22, v22, v23
	v_fmamk_f32 v22, v22, 0x3a800000, v248
	v_mul_f32_e32 v23, 0x4b800000, v22
	v_cmp_gt_f32_e32 vcc, s64, v22
	s_nop 1
	v_cndmask_b32_e32 v22, v22, v23, vcc
	v_rsq_f32_e32 v22, v22
	s_nop 0
	v_mul_f32_e32 v23, 0x45800000, v22
	v_cndmask_b32_e32 v22, v22, v23, vcc
	v_mul_f32_e32 v24, v144, v22
	v_mul_f32_e32 v25, v145, v22
	v_mul_f32_e32 v26, v146, v22
	v_mul_f32_e32 v27, v147, v22
	v_mul_f32_e32 v24, v116, v24
	v_mul_f32_e32 v25, v117, v25
	v_mul_f32_e32 v26, v118, v26
	v_mul_f32_e32 v27, v119, v27
	v_cvt_pk_bf16_f32 v192, v24, v25
	v_cvt_pk_bf16_f32 v193, v26, v27
	v_mul_f32_e32 v24, v148, v22
	v_mul_f32_e32 v25, v149, v22
	v_mul_f32_e32 v26, v150, v22
	v_mul_f32_e32 v27, v151, v22
	v_mul_f32_e32 v24, v120, v24
	v_mul_f32_e32 v25, v121, v25
	v_mul_f32_e32 v26, v122, v26
	v_mul_f32_e32 v27, v123, v27
	v_cvt_pk_bf16_f32 v194, v24, v25
	v_cvt_pk_bf16_f32 v195, v26, v27
	v_mul_f32_e32 v24, v152, v22
	v_mul_f32_e32 v25, v153, v22
	v_mul_f32_e32 v26, v154, v22
	v_mul_f32_e32 v27, v155, v22
	v_mul_f32_e32 v24, v124, v24
	v_mul_f32_e32 v25, v125, v25
	v_mul_f32_e32 v26, v126, v26
	v_mul_f32_e32 v27, v127, v27
	v_cvt_pk_bf16_f32 v196, v24, v25
	v_cvt_pk_bf16_f32 v197, v26, v27
	v_mul_f32_e32 v24, v156, v22
	v_mul_f32_e32 v25, v157, v22
	v_mul_f32_e32 v26, v158, v22
	v_mul_f32_e32 v27, v159, v22
	v_mul_f32_e32 v24, v128, v24
	v_mul_f32_e32 v25, v129, v25
	v_mul_f32_e32 v26, v130, v26
	v_mul_f32_e32 v27, v131, v27
	v_cvt_pk_bf16_f32 v198, v24, v25
	v_cvt_pk_bf16_f32 v199, v26, v27
.Ln14_noh_A:
	s_and_b64 vcc, exec, s[18:19]
	s_cbranch_vccz .Ln14_skipB
	s_waitcnt vmcnt(4)
	v_lshlrev_b32_e32 v44, 16, v184
	v_and_b32_e32 v45, 0xffff0000, v184
	v_lshlrev_b32_e32 v46, 16, v185
	v_and_b32_e32 v47, 0xffff0000, v185
	v_lshlrev_b32_e32 v48, 16, v186
	v_and_b32_e32 v49, 0xffff0000, v186
	v_lshlrev_b32_e32 v50, 16, v187
	v_and_b32_e32 v51, 0xffff0000, v187
	v_lshlrev_b32_e32 v52, 16, v188
	v_and_b32_e32 v53, 0xffff0000, v188
	v_lshlrev_b32_e32 v54, 16, v189
	v_and_b32_e32 v55, 0xffff0000, v189
	v_lshlrev_b32_e32 v60, 16, v190
	v_and_b32_e32 v61, 0xffff0000, v190
	v_lshlrev_b32_e32 v62, 16, v191
	v_and_b32_e32 v63, 0xffff0000, v191
	v_mul_f32_e32 v14, v45, v45
	v_mul_f32_e32 v15, v47, v47
	v_mul_f32_e32 v16, v49, v49
	v_mul_f32_e32 v17, v51, v51
	v_mul_f32_e32 v18, v53, v53
	v_mul_f32_e32 v19, v55, v55
	v_mul_f32_e32 v20, v61, v61
	v_mul_f32_e32 v21, v63, v63
	v_fmac_f32_e32 v14, v44, v44
	v_fmac_f32_e32 v15, v46, v46
	v_fmac_f32_e32 v16, v48, v48
	v_fmac_f32_e32 v17, v50, v50
	v_fmac_f32_e32 v18, v52, v52
	v_fmac_f32_e32 v19, v54, v54
	v_fmac_f32_e32 v20, v60, v60
	v_fmac_f32_e32 v21, v62, v62
	v_add_f32_e32 v14, v14, v15
	v_add_f32_e32 v16, v16, v17
	v_add_f32_e32 v18, v18, v19
	v_add_f32_e32 v20, v20, v21
	v_add_f32_e32 v22, v14, v16
	v_add_f32_e32 v22, v18, v22
	v_add_f32_e32 v22, v20, v22
	s_nop 1
	v_add_f32_dpp v22, v22, v22 quad_perm:[1,0,3,2] row_mask:0xf bank_mask:0xf bound_ctrl:1
	s_nop 1
	v_add_f32_dpp v22, v22, v22 quad_perm:[2,3,0,1] row_mask:0xf bank_mask:0xf bound_ctrl:1
	s_nop 1
	v_add_f32_dpp v22, v22, v22 row_half_mirror row_mask:0xf bank_mask:0xf bound_ctrl:1
	s_nop 1
	v_add_f32_dpp v22, v22, v22 row_mirror row_mask:0xf bank_mask:0xf bound_ctrl:1
	v_mov_b32_e32 v23, v22
	s_nop 1
	v_permlane16_swap_b32_e32 v22, v23
	v_add_f32_e32 v22, v22, v23
	v_mov_b32_e32 v23, v22
	s_nop 1
	v_permlane32_swap_b32_e32 v22, v23
	v_add_f32_e32 v22, v22, v23
	v_fmamk_f32 v22, v22, 0x3a800000, v248
	v_mul_f32_e32 v23, 0x4b800000, v22
	v_cmp_gt_f32_e32 vcc, s64, v22
	s_nop 1
	v_cndmask_b32_e32 v22, v22, v23, vcc
	v_rsq_f32_e32 v22, v22
	s_nop 0
	v_mul_f32_e32 v23, 0x45800000, v22
	v_cndmask_b32_e32 v22, v22, v23, vcc
	v_mul_f32_e32 v22, 0.5, v22
	s_waitcnt vmcnt(0)
	v_mul_f32_e32 v24, v44, v100
	v_mul_f32_e32 v25, v45, v101
	v_mul_f32_e32 v26, v46, v102
	v_mul_f32_e32 v27, v47, v103
	v_fmac_f32_e32 v168, v24, v22
	v_fmac_f32_e32 v169, v25, v22
	v_fmac_f32_e32 v170, v26, v22
	v_fmac_f32_e32 v171, v27, v22
	v_mul_f32_e32 v24, v48, v104
	v_mul_f32_e32 v25, v49, v105
	v_mul_f32_e32 v26, v50, v106
	v_mul_f32_e32 v27, v51, v107
	v_fmac_f32_e32 v172, v24, v22
	v_fmac_f32_e32 v173, v25, v22
	v_fmac_f32_e32 v174, v26, v22
	v_fmac_f32_e32 v175, v27, v22
	v_mul_f32_e32 v24, v52, v108
	v_mul_f32_e32 v25, v53, v109
	v_mul_f32_e32 v26, v54, v110
	v_mul_f32_e32 v27, v55, v111
	v_fmac_f32_e32 v176, v24, v22
	v_fmac_f32_e32 v177, v25, v22
	v_fmac_f32_e32 v178, v26, v22
	v_fmac_f32_e32 v179, v27, v22
	v_mul_f32_e32 v24, v60, v112
	v_mul_f32_e32 v25, v61, v113
	v_mul_f32_e32 v26, v62, v114
	v_mul_f32_e32 v27, v63, v115
	v_fmac_f32_e32 v180, v24, v22
	v_fmac_f32_e32 v181, v25, v22
	v_fmac_f32_e32 v182, v26, v22
	v_fmac_f32_e32 v183, v27, v22
	s_and_b64 vcc, exec, s[28:29]
	s_cbranch_vccz .Ln14_noh_B
; __device__ __forceinline__ unsigned cvt_pk_bf16(float lo, float hi) { f32x2_t v = {lo, hi}; bf16x2_t b = __builtin_convertvector(v, bf16x2_t); return __builtin_bit_cast(unsigned, b); }
; __device__ __forceinline__ void norm_phase(const Ctx& C, int w0, int nw, const float* xin, float* xout, const bf16_t* y, bf16_t* h, const float* gpost, const float* gpre, float coef) {
;     ...
;             if (gpre) {
;                 const float r2 = rsqrtf(wave_sum(s2) * (1.f / DM) + EPS);
;                 u32x2* o = (u32x2*)(h + (size_t)m * DM) + C.lane;
; #pragma unroll
;                 for (int j = 0; j < 4; ++j) { const f32x4 gg = ((const f32x4*)gpre)[C.lane + 64 * j]; u32x2 w; w.x = cvt_pk_bf16(xv[r][j].x * r2 * gg.x, xv[r][j].y * r2 * gg.y); w.y = cvt_pk_bf16(xv[r][j].z * r2 * gg.z, xv[r][j].w * r2 * gg.w); o[64 * j] = w; }
;             }
;         }
;     }
	v_mul_f32_e32 v14, v169, v169
	v_mul_f32_e32 v15, v171, v171
	v_mul_f32_e32 v16, v173, v173
	v_mul_f32_e32 v17, v175, v175
	v_mul_f32_e32 v18, v177, v177
	v_mul_f32_e32 v19, v179, v179
	v_mul_f32_e32 v20, v181, v181
	v_mul_f32_e32 v21, v183, v183
	v_fmac_f32_e32 v14, v168, v168
	v_fmac_f32_e32 v15, v170, v170
	v_fmac_f32_e32 v16, v172, v172
	v_fmac_f32_e32 v17, v174, v174
	v_fmac_f32_e32 v18, v176, v176
	v_fmac_f32_e32 v19, v178, v178
	v_fmac_f32_e32 v20, v180, v180
	v_fmac_f32_e32 v21, v182, v182
	v_add_f32_e32 v14, v14, v15
	v_add_f32_e32 v16, v16, v17
	v_add_f32_e32 v18, v18, v19
	v_add_f32_e32 v20, v20, v21
	v_add_f32_e32 v22, v14, v16
	v_add_f32_e32 v22, v18, v22
	v_add_f32_e32 v22, v20, v22
	s_nop 1
	v_add_f32_dpp v22, v22, v22 quad_perm:[1,0,3,2] row_mask:0xf bank_mask:0xf bound_ctrl:1
	s_nop 1
	v_add_f32_dpp v22, v22, v22 quad_perm:[2,3,0,1] row_mask:0xf bank_mask:0xf bound_ctrl:1
	s_nop 1
	v_add_f32_dpp v22, v22, v22 row_half_mirror row_mask:0xf bank_mask:0xf bound_ctrl:1
	s_nop 1
	v_add_f32_dpp v22, v22, v22 row_mirror row_mask:0xf bank_mask:0xf bound_ctrl:1
	v_mov_b32_e32 v23, v22
	s_nop 1
	v_permlane16_swap_b32_e32 v22, v23
	v_add_f32_e32 v22, v22, v23
	v_mov_b32_e32 v23, v22
	s_nop 1
	v_permlane32_swap_b32_e32 v22, v23
	v_add_f32_e32 v22, v22, v23
	v_fmamk_f32 v22, v22, 0x3a800000, v248
	v_mul_f32_e32 v23, 0x4b800000, v22
	v_cmp_gt_f32_e32 vcc, s64, v22
	s_nop 1
	v_cndmask_b32_e32 v22, v22, v23, vcc
	v_rsq_f32_e32 v22, v22
	s_nop 0
	v_mul_f32_e32 v23, 0x45800000, v22
	v_cndmask_b32_e32 v22, v22, v23, vcc
	v_mul_f32_e32 v24, v168, v22
	v_mul_f32_e32 v25, v169, v22
	v_mul_f32_e32 v26, v170, v22
	v_mul_f32_e32 v27, v171, v22
	v_mul_f32_e32 v24, v116, v24
	v_mul_f32_e32 v25, v117, v25
	v_mul_f32_e32 v26, v118, v26
	v_mul_f32_e32 v27, v119, v27
	v_cvt_pk_bf16_f32 v200, v24, v25
	v_cvt_pk_bf16_f32 v201, v26, v27
	v_mul_f32_e32 v24, v172, v22
	v_mul_f32_e32 v25, v173, v22
	v_mul_f32_e32 v26, v174, v22
	v_mul_f32_e32 v27, v175, v22
	v_mul_f32_e32 v24, v120, v24
	v_mul_f32_e32 v25, v121, v25
	v_mul_f32_e32 v26, v122, v26
	v_mul_f32_e32 v27, v123, v27
	v_cvt_pk_bf16_f32 v202, v24, v25
	v_cvt_pk_bf16_f32 v203, v26, v27
	v_mul_f32_e32 v24, v176, v22
	v_mul_f32_e32 v25, v177, v22
	v_mul_f32_e32 v26, v178, v22
	v_mul_f32_e32 v27, v179, v22
	v_mul_f32_e32 v24, v124, v24
	v_mul_f32_e32 v25, v125, v25
	v_mul_f32_e32 v26, v126, v26
	v_mul_f32_e32 v27, v127, v27
	v_cvt_pk_bf16_f32 v204, v24, v25
	v_cvt_pk_bf16_f32 v205, v26, v27
	v_mul_f32_e32 v24, v180, v22
	v_mul_f32_e32 v25, v181, v22
	v_mul_f32_e32 v26, v182, v22
	v_mul_f32_e32 v27, v183, v22
	v_mul_f32_e32 v24, v128, v24
	v_mul_f32_e32 v25, v129, v25
	v_mul_f32_e32 v26, v130, v26
	v_mul_f32_e32 v27, v131, v27
	v_cvt_pk_bf16_f32 v206, v24, v25
	v_cvt_pk_bf16_f32 v207, v26, v27
.Ln14_noh_B:
.Ln14_skipB:
	global_store_dwordx4 v[28:29], v[144:147], off
	global_store_dwordx4 v[28:29], v[148:151], off offset:1024
	global_store_dwordx4 v[28:29], v[152:155], off offset:2048
	global_store_dwordx4 v[28:29], v[156:159], off offset:3072
	s_and_b64 vcc, exec, s[28:29]
	s_cbranch_vccz .Ln14_nohs_A
	global_store_dwordx2 v[10:11], v[192:193], off
	global_store_dwordx2 v[10:11], v[194:195], off offset:512
	global_store_dwordx2 v[10:11], v[196:197], off offset:1024
	global_store_dwordx2 v[10:11], v[198:199], off offset:1536
.Ln14_nohs_A:
	s_and_b64 vcc, exec, s[18:19]
	s_cbranch_vccz .Ln14_skipBs
	global_store_dwordx4 v[30:31], v[168:171], off
	global_store_dwordx4 v[30:31], v[172:175], off offset:1024
	global_store_dwordx4 v[30:31], v[176:179], off offset:2048
	global_store_dwordx4 v[30:31], v[180:183], off offset:3072
	s_and_b64 vcc, exec, s[28:29]
	s_cbranch_vccz .Ln14_nohs_B
	global_store_dwordx2 v[12:13], v[200:201], off
	global_store_dwordx2 v[12:13], v[202:203], off offset:512
	global_store_dwordx2 v[12:13], v[204:205], off offset:1024
	global_store_dwordx2 v[12:13], v[206:207], off offset:1536
.Ln14_nohs_B:
.Ln14_skipBs:
	s_add_i32 s10, s12, s70
	s_cmp_lt_i32 s10, 0x8000
	s_cbranch_scc1 .Ln14_loop
